# v081 + P7 and last-phase GEMM epilogues: pairs of 8-byte stores merged into one 16-byte store per lane via v_permlane16_swap (half the store instructions)
# speedup vs baseline: 1.0280x; 1.0035x over previous
; #define G_STAGE(bufoff, gbase, voff) do { _Pragma("unroll") for (int _i = 0; _i < 2; ++_i) \
;         __builtin_amdgcn_global_load_lds((const unsigned*)((const char*)(gbase) + (voff)[_i]), (LAS unsigned*)(lds + (bufoff) + ldsw + _i * 8192), 16, 0, 0); } while (0)
; #define G_LDA(dst, b, h) do { _Pragma("unroll") for (int m = 0; m < 4; ++m) _Pragma("unroll") for (int k = 0; k < 2; ++k) dst[m][k] = *(const LAS bf16x8*)(lds + G_SA(b, h) + aoff + m * 2048 + k * 1024); } while (0)
; #define G_LDB(dst, b, h) do { _Pragma("unroll") for (int n = 0; n < 2; ++n) _Pragma("unroll") for (int k = 0; k < 2; ++k) dst[n][k] = *(const LAS bf16x8*)(lds + G_SB(b, h) + boff + n * 2048 + k * 1024); } while (0)
; #define G_MMA(ai, bj, At, Bt) do { __builtin_amdgcn_s_setprio(1); _Pragma("unroll") for (int m = 0; m < 4; ++m) _Pragma("unroll") for (int n = 0; n < 2; ++n) _Pragma("unroll") for (int k = 0; k < 2; ++k) \
;         acc[ai][bj][m][n] = __builtin_amdgcn_mfma_f32_16x16x32_bf16(Bt[n][k], At[m][k], acc[ai][bj][m][n], 0, 0, 0); __builtin_amdgcn_s_setprio(0); } while (0)
; #define G_WAIT_V(n) asm volatile("s_waitcnt vmcnt(" #n ")" ::: "memory")
; #define G_WAIT_L(n) asm volatile("s_waitcnt lgkmcnt(" #n ")" ::: "memory")
; template <bool PERM, class Dec, class Epi>
; DI void gemm_phase(LAS unsigned char* lds, const int nM, const int nN, const int K, const int lda, const int ldb, const Dec& dec, const Epi& epi, const int vb, const int panel = -1) {
;     ...
;         for (int t = 0; t < nt; t += 2) {
;             const bool last = (t == nt - 2);
;             const char* a1 = cA + (size_t)(t + 1) * kstep;
;             const char* a2 = last ? nA : cA + (size_t)(t + 2) * kstep; const char* b2 = last ? nB : cB + (size_t)(t + 2) * kstep;
;             const char* a3 = a2 + kstep; const char* b3 = b2 + kstep;
;             G_LDB(B0, 0, 0); G_SCHED; G_LDA(At, 0, 0); G_STAGE(G_SA(1, 1), a1 + hstepA, voffA);
;             G_WAIT_L(8); G_BAR; G_WAIT_L(0); G_MMA(0, 0, At, B0); G_BAR; G_SCHED;
;             G_LDB(B1, 0, 1); G_STAGE(G_SB(0, 0), b2, voffB);
;             G_BAR; G_WAIT_L(0); G_MMA(0, 1, At, B1); G_BAR;
;             G_LDA(At, 0, 1); G_STAGE(G_SA(0, 0), a2, voffA);
;             G_BAR; G_WAIT_L(0); G_MMA(1, 0, At, B0); G_BAR; G_SCHED;
;             G_STAGE(G_SB(0, 1), b2 + hstepB, voffB);
;             G_WAIT_V(6); G_BAR; G_MMA(1, 1, At, B1); G_BAR;
.LBB0_670:
	s_add_u32 s50, s2, 0xfff80080
	s_addc_u32 s51, s3, -1
	s_add_i32 s64, 0, 0x10000
	v_add_u32_e32 v149, s64, v147
	ds_read_b128 v[142:145], v149
	ds_read_b128 v[150:153], v149 offset:1024
	ds_read_b128 v[154:157], v149 offset:2048
	ds_read_b128 v[158:161], v149 offset:3072
	s_cmp_eq_u32 s75, 28
	s_cselect_b32 s53, s35, s51
	s_cselect_b32 s52, s37, s50
	s_cselect_b32 s51, s71, s74
	s_cselect_b32 s50, s72, s73
	v_lshl_add_u64 v[198:199], s[2:3], 0, v[138:139]
	s_add_i32 m0, s54, 0xc000
	ds_read_b128 v[162:165], v148
	ds_read_b128 v[166:169], v148 offset:1024
	ds_read_b128 v[170:173], v148 offset:2048
	ds_read_b128 v[176:179], v148 offset:3072
	ds_read_b128 v[180:183], v148 offset:4096
	ds_read_b128 v[184:187], v148 offset:5120
	ds_read_b128 v[188:191], v148 offset:6144
	ds_read_b128 v[194:197], v148 offset:7168
	global_load_lds_dwordx4 v[198:199], off
	v_lshl_add_u64 v[198:199], s[2:3], 0, v[140:141]
	s_add_i32 m0, s54, 0xe000
	s_nop 0
	global_load_lds_dwordx4 v[198:199], off
	s_waitcnt lgkmcnt(8)
	s_barrier
	s_waitcnt lgkmcnt(0)
	s_setprio 1
	s_waitcnt lgkmcnt(0)
	v_mfma_f32_16x16x32_bf16 v[124:127], v[142:145], v[162:165], v[124:127]
	v_mfma_f32_16x16x32_bf16 v[120:123], v[154:157], v[162:165], v[120:123]
	v_mfma_f32_16x16x32_bf16 v[108:111], v[142:145], v[170:173], v[108:111]
	v_mfma_f32_16x16x32_bf16 v[104:107], v[154:157], v[170:173], v[104:107]
	v_mfma_f32_16x16x32_bf16 v[92:95], v[142:145], v[180:183], v[92:95]
	v_mfma_f32_16x16x32_bf16 v[88:91], v[154:157], v[180:183], v[88:91]
	v_mfma_f32_16x16x32_bf16 v[76:79], v[142:145], v[188:191], v[76:79]
	v_mfma_f32_16x16x32_bf16 v[72:75], v[154:157], v[188:191], v[72:75]
	v_mfma_f32_16x16x32_bf16 v[124:127], v[150:153], v[166:169], v[124:127]
	v_mfma_f32_16x16x32_bf16 v[120:123], v[158:161], v[166:169], v[120:123]
	v_mfma_f32_16x16x32_bf16 v[108:111], v[150:153], v[176:179], v[108:111]
	v_mfma_f32_16x16x32_bf16 v[104:107], v[158:161], v[176:179], v[104:107]
	v_mfma_f32_16x16x32_bf16 v[92:95], v[150:153], v[184:187], v[92:95]
	v_mfma_f32_16x16x32_bf16 v[88:91], v[158:161], v[184:187], v[88:91]
	v_mfma_f32_16x16x32_bf16 v[76:79], v[150:153], v[194:197], v[76:79]
	v_mfma_f32_16x16x32_bf16 v[72:75], v[158:161], v[194:197], v[72:75]
	s_setprio 0
	s_barrier
	s_add_i32 s68, 0, 0x14000
	s_add_i32 s64, s64, s39
	v_add_u32_e32 v149, s68, v147
	v_lshl_add_u64 v[214:215], s[50:51], 0, v[128:129]
	s_mov_b32 m0, s64
	ds_read_b128 v[198:201], v149
	ds_read_b128 v[202:205], v149 offset:1024
	ds_read_b128 v[206:209], v149 offset:2048
	ds_read_b128 v[210:213], v149 offset:3072
	global_load_lds_dwordx4 v[214:215], off
	v_lshl_add_u64 v[216:217], s[50:51], 0, v[134:135]
	s_add_i32 m0, s64, 0x2000
	s_nop 0
	global_load_lds_dwordx4 v[216:217], off
	s_barrier
	s_waitcnt lgkmcnt(0)
	s_setprio 1
	s_waitcnt lgkmcnt(0)
	v_mfma_f32_16x16x32_bf16 v[116:119], v[198:201], v[162:165], v[116:119]
	v_mfma_f32_16x16x32_bf16 v[112:115], v[206:209], v[162:165], v[112:115]
	v_mfma_f32_16x16x32_bf16 v[100:103], v[198:201], v[170:173], v[100:103]
	v_mfma_f32_16x16x32_bf16 v[96:99], v[206:209], v[170:173], v[96:99]
	v_mfma_f32_16x16x32_bf16 v[84:87], v[198:201], v[180:183], v[84:87]
	v_mfma_f32_16x16x32_bf16 v[80:83], v[206:209], v[180:183], v[80:83]
	v_mfma_f32_16x16x32_bf16 v[68:71], v[198:201], v[188:191], v[68:71]
	v_mfma_f32_16x16x32_bf16 v[64:67], v[206:209], v[188:191], v[64:67]
	v_mfma_f32_16x16x32_bf16 v[116:119], v[202:205], v[166:169], v[116:119]
	v_mfma_f32_16x16x32_bf16 v[112:115], v[210:213], v[166:169], v[112:115]
	v_mfma_f32_16x16x32_bf16 v[100:103], v[202:205], v[176:179], v[100:103]
	v_mfma_f32_16x16x32_bf16 v[96:99], v[210:213], v[176:179], v[96:99]
	v_mfma_f32_16x16x32_bf16 v[84:87], v[202:205], v[184:187], v[84:87]
	v_mfma_f32_16x16x32_bf16 v[80:83], v[210:213], v[184:187], v[80:83]
	v_mfma_f32_16x16x32_bf16 v[68:71], v[202:205], v[194:197], v[68:71]
	v_mfma_f32_16x16x32_bf16 v[64:67], v[210:213], v[194:197], v[64:67]
	s_setprio 0
	s_mov_b32 m0, s54
	v_lshl_add_u64 v[218:219], s[52:53], 0, v[128:129]
	s_barrier
	ds_read_b128 v[162:165], v148 offset:16384
	ds_read_b128 v[166:169], v148 offset:17408
	ds_read_b128 v[170:173], v148 offset:18432
	ds_read_b128 v[176:179], v148 offset:19456
	ds_read_b128 v[180:183], v148 offset:20480
	ds_read_b128 v[184:187], v148 offset:21504
	ds_read_b128 v[188:191], v148 offset:22528
	ds_read_b128 v[194:197], v148 offset:23552
	global_load_lds_dwordx4 v[218:219], off
	v_lshl_add_u64 v[220:221], s[52:53], 0, v[134:135]
	s_mov_b32 m0, s55
	s_nop 0
	global_load_lds_dwordx4 v[220:221], off
	s_barrier
	s_waitcnt lgkmcnt(0)
	s_setprio 1
	s_waitcnt lgkmcnt(0)
	v_mfma_f32_16x16x32_bf16 v[60:63], v[142:145], v[162:165], v[60:63]
	v_mfma_f32_16x16x32_bf16 v[56:59], v[154:157], v[162:165], v[56:59]
	v_mfma_f32_16x16x32_bf16 v[44:47], v[142:145], v[170:173], v[44:47]
	v_mfma_f32_16x16x32_bf16 v[40:43], v[154:157], v[170:173], v[40:43]
	v_mfma_f32_16x16x32_bf16 v[28:31], v[142:145], v[180:183], v[28:31]
	v_mfma_f32_16x16x32_bf16 v[24:27], v[154:157], v[180:183], v[24:27]
	v_mfma_f32_16x16x32_bf16 v[12:15], v[142:145], v[188:191], v[12:15]
	v_mfma_f32_16x16x32_bf16 v[8:11], v[154:157], v[188:191], v[8:11]
	v_mfma_f32_16x16x32_bf16 v[60:63], v[150:153], v[166:169], v[60:63]
	v_mfma_f32_16x16x32_bf16 v[56:59], v[158:161], v[166:169], v[56:59]
	v_mfma_f32_16x16x32_bf16 v[44:47], v[150:153], v[176:179], v[44:47]
	v_mfma_f32_16x16x32_bf16 v[40:43], v[158:161], v[176:179], v[40:43]
	v_mfma_f32_16x16x32_bf16 v[28:31], v[150:153], v[184:187], v[28:31]
	v_mfma_f32_16x16x32_bf16 v[24:27], v[158:161], v[184:187], v[24:27]
	v_mfma_f32_16x16x32_bf16 v[12:15], v[150:153], v[194:197], v[12:15]
	v_mfma_f32_16x16x32_bf16 v[8:11], v[158:161], v[194:197], v[8:11]
	s_setprio 0
	s_barrier
; #define G_STAGE(bufoff, gbase, voff) do { _Pragma("unroll") for (int _i = 0; _i < 2; ++_i) \
;         __builtin_amdgcn_global_load_lds((const unsigned*)((const char*)(gbase) + (voff)[_i]), (LAS unsigned*)(lds + (bufoff) + ldsw + _i * 8192), 16, 0, 0); } while (0)
; #define G_LDA(dst, b, h) do { _Pragma("unroll") for (int m = 0; m < 4; ++m) _Pragma("unroll") for (int k = 0; k < 2; ++k) dst[m][k] = *(const LAS bf16x8*)(lds + G_SA(b, h) + aoff + m * 2048 + k * 1024); } while (0)
; #define G_LDB(dst, b, h) do { _Pragma("unroll") for (int n = 0; n < 2; ++n) _Pragma("unroll") for (int k = 0; k < 2; ++k) dst[n][k] = *(const LAS bf16x8*)(lds + G_SB(b, h) + boff + n * 2048 + k * 1024); } while (0)
; #define G_MMA(ai, bj, At, Bt) do { __builtin_amdgcn_s_setprio(1); _Pragma("unroll") for (int m = 0; m < 4; ++m) _Pragma("unroll") for (int n = 0; n < 2; ++n) _Pragma("unroll") for (int k = 0; k < 2; ++k) \
;         acc[ai][bj][m][n] = __builtin_amdgcn_mfma_f32_16x16x32_bf16(Bt[n][k], At[m][k], acc[ai][bj][m][n], 0, 0, 0); __builtin_amdgcn_s_setprio(0); } while (0)
; #define G_WAIT_V(n) asm volatile("s_waitcnt vmcnt(" #n ")" ::: "memory")
; #define G_WAIT_L(n) asm volatile("s_waitcnt lgkmcnt(" #n ")" ::: "memory")
; #define G_BAR __builtin_amdgcn_s_barrier()
; #define G_SCHED __builtin_amdgcn_sched_barrier(0)
; template <bool PERM, class Dec, class Epi>
; DI void gemm_phase(LAS unsigned char* lds, const int nM, const int nN, const int K, const int lda, const int ldb, const Dec& dec, const Epi& epi, const int vb, const int panel = -1) {
;     ...
;             G_STAGE(G_SB(0, 1), b2 + hstepB, voffB);
;             G_WAIT_V(6); G_BAR; G_MMA(1, 1, At, B1); G_BAR;
;             G_LDB(B0, 1, 0); G_SCHED; G_LDA(At, 1, 0); G_STAGE(G_SA(0, 1), a2 + hstepA, voffA);
;             G_WAIT_L(8); G_BAR; G_WAIT_L(0); G_MMA(0, 0, At, B0); G_BAR; G_SCHED;
;             G_LDB(B1, 1, 1); G_STAGE(G_SB(1, 0), b3, voffB);
;             G_BAR; G_WAIT_L(0); G_MMA(0, 1, At, B1); G_BAR;
;             G_LDA(At, 1, 1); G_STAGE(G_SA(1, 0), a3, voffA);
;             G_BAR; G_WAIT_L(0); G_MMA(1, 0, At, B0); G_BAR; G_SCHED;
	s_add_u32 s64, s50, 0x80000
	s_addc_u32 s65, s51, 0
	s_add_i32 s68, s68, s39
	v_lshl_add_u64 v[142:143], s[64:65], 0, v[128:129]
	s_mov_b32 m0, s68
	s_nop 0
	global_load_lds_dwordx4 v[142:143], off
	v_lshl_add_u64 v[142:143], s[64:65], 0, v[134:135]
	s_add_i32 m0, s68, 0x2000
	s_nop 0
	global_load_lds_dwordx4 v[142:143], off
	s_waitcnt vmcnt(6)
	s_barrier
	s_setprio 1
	v_mfma_f32_16x16x32_bf16 v[52:55], v[198:201], v[162:165], v[52:55]
	v_mfma_f32_16x16x32_bf16 v[48:51], v[206:209], v[162:165], v[48:51]
	v_mfma_f32_16x16x32_bf16 v[36:39], v[198:201], v[170:173], v[36:39]
	v_mfma_f32_16x16x32_bf16 v[32:35], v[206:209], v[170:173], v[32:35]
	v_mfma_f32_16x16x32_bf16 v[20:23], v[198:201], v[180:183], v[20:23]
	v_mfma_f32_16x16x32_bf16 v[16:19], v[206:209], v[180:183], v[16:19]
	v_mfma_f32_16x16x32_bf16 v[4:7], v[198:201], v[188:191], v[4:7]
	v_mfma_f32_16x16x32_bf16 v[0:3], v[206:209], v[188:191], v[0:3]
	v_mfma_f32_16x16x32_bf16 v[52:55], v[202:205], v[166:169], v[52:55]
	v_mfma_f32_16x16x32_bf16 v[48:51], v[210:213], v[166:169], v[48:51]
	v_mfma_f32_16x16x32_bf16 v[36:39], v[202:205], v[176:179], v[36:39]
	v_mfma_f32_16x16x32_bf16 v[32:35], v[210:213], v[176:179], v[32:35]
	v_mfma_f32_16x16x32_bf16 v[20:23], v[202:205], v[184:187], v[20:23]
	v_mfma_f32_16x16x32_bf16 v[16:19], v[210:213], v[184:187], v[16:19]
	v_mfma_f32_16x16x32_bf16 v[4:7], v[202:205], v[194:197], v[4:7]
	v_mfma_f32_16x16x32_bf16 v[0:3], v[210:213], v[194:197], v[0:3]
	s_setprio 0
	s_add_i32 s64, 0, 0x18000
	v_add_u32_e32 v149, s64, v147
	s_barrier
	ds_read_b128 v[142:145], v149
	ds_read_b128 v[150:153], v149 offset:1024
	ds_read_b128 v[154:157], v149 offset:2048
	ds_read_b128 v[158:161], v149 offset:3072
	s_add_u32 s52, s52, 0x80000
	s_addc_u32 s53, s53, 0
	s_mov_b32 m0, s58
	v_lshl_add_u64 v[198:199], s[52:53], 0, v[128:129]
	ds_read_b128 v[162:165], v148 offset:32768
	ds_read_b128 v[166:169], v148 offset:33792
	ds_read_b128 v[170:173], v148 offset:34816
	ds_read_b128 v[176:179], v148 offset:35840
	ds_read_b128 v[180:183], v148 offset:36864
	ds_read_b128 v[184:187], v148 offset:37888
	ds_read_b128 v[188:191], v148 offset:38912
	ds_read_b128 v[194:197], v148 offset:39936
	global_load_lds_dwordx4 v[198:199], off
	v_lshl_add_u64 v[198:199], s[52:53], 0, v[134:135]
	s_mov_b32 m0, s59
	s_nop 0
	global_load_lds_dwordx4 v[198:199], off
	s_waitcnt lgkmcnt(8)
	s_barrier
	s_waitcnt lgkmcnt(0)
	s_setprio 1
	s_waitcnt lgkmcnt(0)
	v_mfma_f32_16x16x32_bf16 v[124:127], v[142:145], v[162:165], v[124:127]
	v_mfma_f32_16x16x32_bf16 v[120:123], v[154:157], v[162:165], v[120:123]
	v_mfma_f32_16x16x32_bf16 v[108:111], v[142:145], v[170:173], v[108:111]
	v_mfma_f32_16x16x32_bf16 v[104:107], v[154:157], v[170:173], v[104:107]
	v_mfma_f32_16x16x32_bf16 v[92:95], v[142:145], v[180:183], v[92:95]
	v_mfma_f32_16x16x32_bf16 v[88:91], v[154:157], v[180:183], v[88:91]
	v_mfma_f32_16x16x32_bf16 v[76:79], v[142:145], v[188:191], v[76:79]
	v_mfma_f32_16x16x32_bf16 v[72:75], v[154:157], v[188:191], v[72:75]
	v_mfma_f32_16x16x32_bf16 v[124:127], v[150:153], v[166:169], v[124:127]
	v_mfma_f32_16x16x32_bf16 v[120:123], v[158:161], v[166:169], v[120:123]
	v_mfma_f32_16x16x32_bf16 v[108:111], v[150:153], v[176:179], v[108:111]
	v_mfma_f32_16x16x32_bf16 v[104:107], v[158:161], v[176:179], v[104:107]
	v_mfma_f32_16x16x32_bf16 v[92:95], v[150:153], v[184:187], v[92:95]
	v_mfma_f32_16x16x32_bf16 v[88:91], v[158:161], v[184:187], v[88:91]
	v_mfma_f32_16x16x32_bf16 v[76:79], v[150:153], v[194:197], v[76:79]
	v_mfma_f32_16x16x32_bf16 v[72:75], v[158:161], v[194:197], v[72:75]
	s_setprio 0
	s_barrier
	s_add_i32 s52, 0, 0x1c000
	s_add_i32 s53, s64, s39
	v_add_u32_e32 v149, s52, v147
	v_lshl_add_u64 v[214:215], v[214:215], 0, s[30:31]
	s_mov_b32 m0, s53
	ds_read_b128 v[198:201], v149
	ds_read_b128 v[202:205], v149 offset:1024
	ds_read_b128 v[206:209], v149 offset:2048
	ds_read_b128 v[210:213], v149 offset:3072
	global_load_lds_dwordx4 v[214:215], off
	v_lshl_add_u64 v[214:215], v[216:217], 0, s[30:31]
	s_add_i32 m0, s53, 0x2000
	s_nop 0
	global_load_lds_dwordx4 v[214:215], off
	s_barrier
	s_waitcnt lgkmcnt(0)
	s_setprio 1
	s_waitcnt lgkmcnt(0)
	v_mfma_f32_16x16x32_bf16 v[116:119], v[198:201], v[162:165], v[116:119]
	v_mfma_f32_16x16x32_bf16 v[112:115], v[206:209], v[162:165], v[112:115]
	v_mfma_f32_16x16x32_bf16 v[100:103], v[198:201], v[170:173], v[100:103]
	v_mfma_f32_16x16x32_bf16 v[96:99], v[206:209], v[170:173], v[96:99]
	v_mfma_f32_16x16x32_bf16 v[84:87], v[198:201], v[180:183], v[84:87]
	v_mfma_f32_16x16x32_bf16 v[80:83], v[206:209], v[180:183], v[80:83]
	v_mfma_f32_16x16x32_bf16 v[68:71], v[198:201], v[188:191], v[68:71]
	v_mfma_f32_16x16x32_bf16 v[64:67], v[206:209], v[188:191], v[64:67]
	v_mfma_f32_16x16x32_bf16 v[116:119], v[202:205], v[166:169], v[116:119]
	v_mfma_f32_16x16x32_bf16 v[112:115], v[210:213], v[166:169], v[112:115]
	v_mfma_f32_16x16x32_bf16 v[100:103], v[202:205], v[176:179], v[100:103]
	v_mfma_f32_16x16x32_bf16 v[96:99], v[210:213], v[176:179], v[96:99]
	v_mfma_f32_16x16x32_bf16 v[84:87], v[202:205], v[184:187], v[84:87]
	v_mfma_f32_16x16x32_bf16 v[80:83], v[210:213], v[184:187], v[80:83]
	v_mfma_f32_16x16x32_bf16 v[68:71], v[202:205], v[194:197], v[68:71]
	v_mfma_f32_16x16x32_bf16 v[64:67], v[210:213], v[194:197], v[64:67]
	s_setprio 0
	s_mov_b32 m0, s62
	v_lshl_add_u64 v[214:215], v[218:219], 0, s[30:31]
	s_barrier
	ds_read_b128 v[162:165], v148 offset:49152
	ds_read_b128 v[166:169], v148 offset:50176
	ds_read_b128 v[170:173], v148 offset:51200
	ds_read_b128 v[176:179], v148 offset:52224
	ds_read_b128 v[180:183], v148 offset:53248
	ds_read_b128 v[184:187], v148 offset:54272
	ds_read_b128 v[188:191], v148 offset:55296
	ds_read_b128 v[194:197], v148 offset:56320
	global_load_lds_dwordx4 v[214:215], off
	v_lshl_add_u64 v[214:215], v[220:221], 0, s[30:31]
	s_mov_b32 m0, s63
	s_nop 0
	global_load_lds_dwordx4 v[214:215], off
	s_barrier
; #define G_STAGE(bufoff, gbase, voff) do { _Pragma("unroll") for (int _i = 0; _i < 2; ++_i) \
;         __builtin_amdgcn_global_load_lds((const unsigned*)((const char*)(gbase) + (voff)[_i]), (LAS unsigned*)(lds + (bufoff) + ldsw + _i * 8192), 16, 0, 0); } while (0)
; #define G_LDA(dst, b, h) do { _Pragma("unroll") for (int m = 0; m < 4; ++m) _Pragma("unroll") for (int k = 0; k < 2; ++k) dst[m][k] = *(const LAS bf16x8*)(lds + G_SA(b, h) + aoff + m * 2048 + k * 1024); } while (0)
; #define G_LDB(dst, b, h) do { _Pragma("unroll") for (int n = 0; n < 2; ++n) _Pragma("unroll") for (int k = 0; k < 2; ++k) dst[n][k] = *(const LAS bf16x8*)(lds + G_SB(b, h) + boff + n * 2048 + k * 1024); } while (0)
; #define G_WAIT_V(n) asm volatile("s_waitcnt vmcnt(" #n ")" ::: "memory")
; #define G_WAIT_L(n) asm volatile("s_waitcnt lgkmcnt(" #n ")" ::: "memory")
; template <bool PERM, class Dec, class Epi>
; DI void gemm_phase(LAS unsigned char* lds, const int nM, const int nN, const int K, const int lda, const int ldb, const Dec& dec, const Epi& epi, const int vb, const int panel = -1) {
;     ...
;             G_LDB(B0, 1, 0); G_SCHED; G_LDA(At, 1, 0); G_STAGE(G_SA(0, 1), a2 + hstepA, voffA);
;             G_WAIT_L(8); G_BAR; G_WAIT_L(0); G_MMA(0, 0, At, B0); G_BAR; G_SCHED;
;             G_LDB(B1, 1, 1); G_STAGE(G_SB(1, 0), b3, voffB);
;             G_BAR; G_WAIT_L(0); G_MMA(0, 1, At, B1); G_BAR;
;             G_LDA(At, 1, 1); G_STAGE(G_SA(1, 0), a3, voffA);
;             G_BAR; G_WAIT_L(0); G_MMA(1, 0, At, B0); G_BAR; G_SCHED;
;             G_STAGE(G_SB(1, 1), b3 + hstepB, voffB);
;             G_WAIT_V(6); G_BAR; G_MMA(1, 1, At, B1); G_BAR;
;         }
; __global__ void __launch_bounds__(512) hybrid_fwd(Params p) {
;     ...
;           [=](const f32x4 (&acc)[2][2][4][2], int pm, int pn, int wr, int wc, int fr, int fq) {
; #pragma unroll
;               for (int ai = 0; ai < 2; ++ai)
; #pragma unroll
;                   for (int m = 0; m < 4; ++m) { const int row = pm * 256 + ai * 128 + wr * 64 + m * 16 + fr; const size_t ro = (size_t)row * 1024 + pn * 256 + wc * 32 + 4 * fq;
;                       float ssq = 0.f;
; #pragma unroll
;                       for (int bj = 0; bj < 2; ++bj)
; #pragma unroll
;                           for (int n = 0; n < 2; ++n) { const size_t o = ro + bj * 128 + n * 16; const f32x4 v = *(const f32x4*)(X + o) + acc[ai][bj][m][n];
	s_waitcnt lgkmcnt(0)
	s_setprio 1
	s_waitcnt lgkmcnt(0)
	v_mfma_f32_16x16x32_bf16 v[60:63], v[142:145], v[162:165], v[60:63]
	v_mfma_f32_16x16x32_bf16 v[56:59], v[154:157], v[162:165], v[56:59]
	v_mfma_f32_16x16x32_bf16 v[44:47], v[142:145], v[170:173], v[44:47]
	v_mfma_f32_16x16x32_bf16 v[40:43], v[154:157], v[170:173], v[40:43]
	v_mfma_f32_16x16x32_bf16 v[28:31], v[142:145], v[180:183], v[28:31]
	v_mfma_f32_16x16x32_bf16 v[24:27], v[154:157], v[180:183], v[24:27]
	v_mfma_f32_16x16x32_bf16 v[12:15], v[142:145], v[188:191], v[12:15]
	v_mfma_f32_16x16x32_bf16 v[8:11], v[154:157], v[188:191], v[8:11]
	v_mfma_f32_16x16x32_bf16 v[60:63], v[150:153], v[166:169], v[60:63]
	v_mfma_f32_16x16x32_bf16 v[56:59], v[158:161], v[166:169], v[56:59]
	v_mfma_f32_16x16x32_bf16 v[44:47], v[150:153], v[176:179], v[44:47]
	v_mfma_f32_16x16x32_bf16 v[40:43], v[158:161], v[176:179], v[40:43]
	v_mfma_f32_16x16x32_bf16 v[28:31], v[150:153], v[184:187], v[28:31]
	v_mfma_f32_16x16x32_bf16 v[24:27], v[158:161], v[184:187], v[24:27]
	v_mfma_f32_16x16x32_bf16 v[12:15], v[150:153], v[194:197], v[12:15]
	v_mfma_f32_16x16x32_bf16 v[8:11], v[158:161], v[194:197], v[8:11]
	s_setprio 0
	s_barrier
	s_add_u32 s50, s50, 0x80080
	s_addc_u32 s51, s51, 0
	s_add_i32 s52, s52, s39
	v_lshl_add_u64 v[142:143], s[50:51], 0, v[128:129]
	s_mov_b32 m0, s52
	s_nop 0
	global_load_lds_dwordx4 v[142:143], off
	v_lshl_add_u64 v[142:143], s[50:51], 0, v[134:135]
	s_add_i32 m0, s52, 0x2000
	s_nop 0
	global_load_lds_dwordx4 v[142:143], off
	s_waitcnt vmcnt(6)
	s_barrier
	s_setprio 1
	v_mfma_f32_16x16x32_bf16 v[52:55], v[198:201], v[162:165], v[52:55]
	v_mfma_f32_16x16x32_bf16 v[48:51], v[206:209], v[162:165], v[48:51]
	v_mfma_f32_16x16x32_bf16 v[36:39], v[198:201], v[170:173], v[36:39]
	v_mfma_f32_16x16x32_bf16 v[32:35], v[206:209], v[170:173], v[32:35]
	v_mfma_f32_16x16x32_bf16 v[20:23], v[198:201], v[180:183], v[20:23]
	v_mfma_f32_16x16x32_bf16 v[16:19], v[206:209], v[180:183], v[16:19]
	v_mfma_f32_16x16x32_bf16 v[4:7], v[198:201], v[188:191], v[4:7]
	v_mfma_f32_16x16x32_bf16 v[0:3], v[206:209], v[188:191], v[0:3]
	v_mfma_f32_16x16x32_bf16 v[52:55], v[202:205], v[166:169], v[52:55]
	v_mfma_f32_16x16x32_bf16 v[48:51], v[210:213], v[166:169], v[48:51]
	v_mfma_f32_16x16x32_bf16 v[36:39], v[202:205], v[176:179], v[36:39]
	v_mfma_f32_16x16x32_bf16 v[32:35], v[210:213], v[176:179], v[32:35]
	v_mfma_f32_16x16x32_bf16 v[20:23], v[202:205], v[184:187], v[20:23]
	v_mfma_f32_16x16x32_bf16 v[16:19], v[210:213], v[184:187], v[16:19]
	v_mfma_f32_16x16x32_bf16 v[4:7], v[202:205], v[194:197], v[4:7]
	v_mfma_f32_16x16x32_bf16 v[0:3], v[210:213], v[194:197], v[0:3]
	s_setprio 0
	s_add_i32 s75, s75, 2
	s_add_u32 s2, s2, 0x100
	s_addc_u32 s3, s3, 0
	s_add_u32 s73, s73, 0x100
	s_addc_u32 s74, s74, 0
	s_cmp_gt_u32 s75, 29
	s_barrier
	s_cbranch_scc0 .LBB0_670
	v_and_b32_e32 v149, 64, v174
	v_xor_b32_e32 v145, 16, v174
	v_add_u32_e32 v149, 64, v149
	v_cmp_lt_i32_e32 vcc, v145, v149
	v_lshl_add_u32 v144, s67, 8, v146
	s_lshl_b32 s2, s70, 8
	v_cndmask_b32_e32 v145, v174, v145, vcc
	v_lshlrev_b32_e32 v150, 2, v145
	v_xor_b32_e32 v145, 32, v174
	v_cmp_lt_i32_e32 vcc, v145, v149
	s_ashr_i32 s3, s2, 31
	v_mov_b32_e32 v143, s3
	v_cndmask_b32_e32 v145, v174, v145, vcc
	v_lshlrev_b32_e32 v149, 2, v145
	v_ashrrev_i32_e32 v145, 31, v144
	v_or_b32_e32 v142, s2, v136
	v_lshlrev_b64 v[152:153], 10, v[144:145]
	v_readlane_b32 s0, v246, 53
	v_lshl_add_u64 v[156:157], v[152:153], 0, v[142:143]
	v_readlane_b32 s1, v246, 54
	v_readlane_b32 s2, v246, 55
	v_readlane_b32 s3, v246, 56
	v_lshl_add_u64 v[158:159], v[156:157], 2, s[0:1]
	global_load_dwordx4 v[160:163], v[158:159], off
	global_load_dwordx4 v[164:167], v[158:159], off offset:64
	global_load_dwordx4 v[168:171], v[158:159], off offset:512
	global_load_dwordx4 v[176:179], v[158:159], off offset:576
	v_add_co_u32_e32 v214, vcc, 0x10000, v158
	s_nop 1
	v_addc_co_u32_e32 v215, vcc, 0, v159, vcc
	global_load_dwordx4 v[180:183], v[214:215], off
	global_load_dwordx4 v[184:187], v[214:215], off offset:64
	global_load_dwordx4 v[188:191], v[214:215], off offset:512
	global_load_dwordx4 v[194:197], v[214:215], off offset:576
	v_add_co_u32_e32 v214, vcc, 0x20000, v158
	s_nop 1
	v_addc_co_u32_e32 v215, vcc, 0, v159, vcc
	global_load_dwordx4 v[198:201], v[214:215], off
	global_load_dwordx4 v[202:205], v[214:215], off offset:64
	global_load_dwordx4 v[206:209], v[214:215], off offset:512
	global_load_dwordx4 v[210:213], v[214:215], off offset:576
	s_waitcnt vmcnt(8)
	v_pk_add_f32 v[124:125], v[124:125], v[160:161]
	v_pk_add_f32 v[126:127], v[126:127], v[162:163]
	v_pk_add_f32 v[120:121], v[120:121], v[164:165]
	v_pk_add_f32 v[122:123], v[122:123], v[166:167]
	v_pk_add_f32 v[116:117], v[116:117], v[168:169]
	v_pk_add_f32 v[118:119], v[118:119], v[170:171]
	v_pk_add_f32 v[112:113], v[112:113], v[176:177]
	v_pk_add_f32 v[114:115], v[114:115], v[178:179]
	v_add_co_u32_e32 v214, vcc, 0x30000, v158
	s_nop 1
	v_addc_co_u32_e32 v215, vcc, 0, v159, vcc
	global_load_dwordx4 v[160:163], v[214:215], off
	global_load_dwordx4 v[164:167], v[214:215], off offset:64
	global_load_dwordx4 v[168:171], v[214:215], off offset:512
	global_load_dwordx4 v[176:179], v[214:215], off offset:576
	s_waitcnt vmcnt(8)
	v_pk_add_f32 v[108:109], v[108:109], v[180:181]
	v_pk_add_f32 v[110:111], v[110:111], v[182:183]
	v_pk_add_f32 v[104:105], v[104:105], v[184:185]
	v_pk_add_f32 v[106:107], v[106:107], v[186:187]
	v_pk_add_f32 v[100:101], v[100:101], v[188:189]
	v_pk_add_f32 v[102:103], v[102:103], v[190:191]
	v_pk_add_f32 v[96:97], v[96:97], v[194:195]
	v_pk_add_f32 v[98:99], v[98:99], v[196:197]
	v_add_co_u32_e32 v214, vcc, 0x80000, v158
	s_nop 1
	v_addc_co_u32_e32 v215, vcc, 0, v159, vcc
	global_load_dwordx4 v[180:183], v[214:215], off
	global_load_dwordx4 v[184:187], v[214:215], off offset:64
	global_load_dwordx4 v[188:191], v[214:215], off offset:512
	global_load_dwordx4 v[194:197], v[214:215], off offset:576
	s_waitcnt vmcnt(8)
; DI unsigned pk2(float a, float b) { f32x2 v = {a, b}; bf2_t r = __builtin_convertvector(v, bf2_t); return __builtin_bit_cast(unsigned, r); }
; __global__ void __launch_bounds__(512) hybrid_fwd(Params p) {
;     ...
;                           for (int n = 0; n < 2; ++n) { const size_t o = ro + bj * 128 + n * 16; const f32x4 v = *(const f32x4*)(X + o) + acc[ai][bj][m][n];
;                               u32x2 wv; wv[0] = pk2(v[0], v[1]); wv[1] = pk2(v[2], v[3]); *(u32x2*)(U + o) = wv;
;                               ssq += v[0] * v[0] + v[1] * v[1] + v[2] * v[2] + v[3] * v[3]; }
;                       ssq += __shfl_xor(ssq, 16); ssq += __shfl_xor(ssq, 32);
;                       if (fq == 0) unsafeAtomicAdd(SS1 + row, ssq); } }, vb); }
	v_pk_add_f32 v[92:93], v[92:93], v[198:199]
	v_pk_add_f32 v[94:95], v[94:95], v[200:201]
	v_pk_add_f32 v[88:89], v[88:89], v[202:203]
	v_pk_add_f32 v[90:91], v[90:91], v[204:205]
	v_pk_add_f32 v[84:85], v[84:85], v[206:207]
	v_pk_add_f32 v[86:87], v[86:87], v[208:209]
	v_pk_add_f32 v[80:81], v[80:81], v[210:211]
	v_pk_add_f32 v[82:83], v[82:83], v[212:213]
	v_add_co_u32_e32 v214, vcc, 0x90000, v158
	s_nop 1
	v_addc_co_u32_e32 v215, vcc, 0, v159, vcc
	global_load_dwordx4 v[198:201], v[214:215], off
	global_load_dwordx4 v[202:205], v[214:215], off offset:64
	global_load_dwordx4 v[206:209], v[214:215], off offset:512
	global_load_dwordx4 v[210:213], v[214:215], off offset:576
	s_waitcnt vmcnt(8)
	v_pk_add_f32 v[76:77], v[76:77], v[160:161]
	v_pk_add_f32 v[78:79], v[78:79], v[162:163]
	v_pk_add_f32 v[72:73], v[72:73], v[164:165]
	v_pk_add_f32 v[74:75], v[74:75], v[166:167]
	v_pk_add_f32 v[68:69], v[68:69], v[168:169]
	v_pk_add_f32 v[70:71], v[70:71], v[170:171]
	v_pk_add_f32 v[64:65], v[64:65], v[176:177]
	v_pk_add_f32 v[66:67], v[66:67], v[178:179]
	v_add_co_u32_e32 v214, vcc, 0xa0000, v158
	s_nop 1
	v_addc_co_u32_e32 v215, vcc, 0, v159, vcc
	global_load_dwordx4 v[160:163], v[214:215], off
	global_load_dwordx4 v[164:167], v[214:215], off offset:64
	global_load_dwordx4 v[168:171], v[214:215], off offset:512
	global_load_dwordx4 v[176:179], v[214:215], off offset:576
	s_waitcnt vmcnt(8)
	v_pk_add_f32 v[60:61], v[60:61], v[180:181]
	v_pk_add_f32 v[62:63], v[62:63], v[182:183]
	v_pk_add_f32 v[56:57], v[56:57], v[184:185]
	v_pk_add_f32 v[58:59], v[58:59], v[186:187]
	v_pk_add_f32 v[52:53], v[52:53], v[188:189]
	v_pk_add_f32 v[54:55], v[54:55], v[190:191]
	v_pk_add_f32 v[48:49], v[48:49], v[194:195]
	v_pk_add_f32 v[50:51], v[50:51], v[196:197]
	v_add_co_u32_e32 v214, vcc, 0xb0000, v158
	s_nop 1
	v_addc_co_u32_e32 v215, vcc, 0, v159, vcc
	global_load_dwordx4 v[180:183], v[214:215], off
	global_load_dwordx4 v[184:187], v[214:215], off offset:64
	global_load_dwordx4 v[188:191], v[214:215], off offset:512
	global_load_dwordx4 v[194:197], v[214:215], off offset:576
	s_waitcnt vmcnt(8)
	v_pk_add_f32 v[44:45], v[44:45], v[198:199]
	v_pk_add_f32 v[46:47], v[46:47], v[200:201]
	v_pk_add_f32 v[40:41], v[40:41], v[202:203]
	v_pk_add_f32 v[42:43], v[42:43], v[204:205]
	v_pk_add_f32 v[36:37], v[36:37], v[206:207]
	v_pk_add_f32 v[38:39], v[38:39], v[208:209]
	v_pk_add_f32 v[32:33], v[32:33], v[210:211]
	v_pk_add_f32 v[34:35], v[34:35], v[212:213]
	s_waitcnt vmcnt(4)
	v_pk_add_f32 v[28:29], v[28:29], v[160:161]
	v_pk_add_f32 v[30:31], v[30:31], v[162:163]
	v_pk_add_f32 v[24:25], v[24:25], v[164:165]
	v_pk_add_f32 v[26:27], v[26:27], v[166:167]
	v_pk_add_f32 v[20:21], v[20:21], v[168:169]
	v_pk_add_f32 v[22:23], v[22:23], v[170:171]
	v_pk_add_f32 v[16:17], v[16:17], v[176:177]
	v_pk_add_f32 v[18:19], v[18:19], v[178:179]
	s_waitcnt vmcnt(0)
	v_pk_add_f32 v[12:13], v[12:13], v[180:181]
	v_pk_add_f32 v[14:15], v[14:15], v[182:183]
	v_pk_add_f32 v[8:9], v[8:9], v[184:185]
	v_pk_add_f32 v[10:11], v[10:11], v[186:187]
	v_pk_add_f32 v[4:5], v[4:5], v[188:189]
	v_pk_add_f32 v[6:7], v[6:7], v[190:191]
	v_pk_add_f32 v[0:1], v[0:1], v[194:195]
	v_pk_add_f32 v[2:3], v[2:3], v[196:197]
	v_mbcnt_lo_u32_b32 v212, -1, 0
	v_mbcnt_hi_u32_b32 v212, -1, v212
	v_bfe_u32 v212, v212, 4, 1
	v_mul_u32_u24_e32 v212, 24, v212
	v_mov_b32_e32 v213, 0
	v_readlane_b32 s4, v246, 57
	v_readlane_b32 s5, v246, 58
	v_readlane_b32 s6, v246, 59
	v_readlane_b32 s7, v246, 60
	v_readlane_b32 s8, v246, 61
	v_readlane_b32 s9, v246, 62
	v_readlane_b32 s10, v246, 63
	v_readlane_b32 s11, v245, 0
	v_readlane_b32 s12, v245, 1
	v_readlane_b32 s13, v245, 2
	v_readlane_b32 s14, v245, 3
	v_readlane_b32 s15, v245, 4
	v_lshlrev_b64 v[154:155], 1, v[156:157]
	v_mul_f32_e32 v151, v125, v125
	v_cvt_pk_bf16_f32 v152, v124, v125
	v_cvt_pk_bf16_f32 v153, v126, v127
	v_lshl_add_u64 v[156:157], s[20:21], 0, v[154:155]
	v_fmac_f32_e32 v151, v124, v124
	v_mov_b32_e32 v160, v152
	v_mov_b32_e32 v161, v153
	v_lshl_add_u64 v[164:165], v[156:157], 0, v[212:213]
	v_fmac_f32_e32 v151, v126, v126
	v_fmac_f32_e32 v151, v127, v127
	s_nop 0
	v_cvt_pk_bf16_f32 v124, v120, v121
	v_mul_f32_e32 v121, v121, v121
	v_or_b32_e32 v126, 32, v154
	v_mov_b32_e32 v127, v155
	v_fmac_f32_e32 v121, v120, v120
	v_cvt_pk_bf16_f32 v125, v122, v123
	v_lshl_add_u64 v[126:127], s[20:21], 0, v[126:127]
	v_fmac_f32_e32 v121, v122, v122
	v_mov_b32_e32 v162, v124
	v_mov_b32_e32 v163, v125
	s_nop 1
	v_permlane16_swap_b32_e32 v160, v162
	v_permlane16_swap_b32_e32 v161, v163
	global_store_dwordx4 v[164:165], v[160:163], off
	v_fmac_f32_e32 v121, v123, v123
	v_add_f32_e32 v124, v151, v121
	s_nop 0
	v_cvt_pk_bf16_f32 v120, v116, v117
	v_mul_f32_e32 v117, v117, v117
	v_or_b32_e32 v122, 0x100, v154
	v_mov_b32_e32 v123, v155
	v_fmac_f32_e32 v117, v116, v116
	v_cvt_pk_bf16_f32 v121, v118, v119
	v_lshl_add_u64 v[122:123], s[20:21], 0, v[122:123]
	v_fmac_f32_e32 v117, v118, v118
	v_mov_b32_e32 v168, v120
	v_mov_b32_e32 v169, v121
	v_lshl_add_u64 v[166:167], v[122:123], 0, v[212:213]
	v_fmac_f32_e32 v117, v119, v119
	v_add_f32_e32 v120, v124, v117
	v_or_b32_e32 v154, 0x120, v154
	s_nop 0
	v_cvt_pk_bf16_f32 v116, v112, v113
	v_mul_f32_e32 v113, v113, v113
	v_fmac_f32_e32 v113, v112, v112
	v_fmac_f32_e32 v113, v114, v114
	v_fmac_f32_e32 v113, v115, v115
	v_add_f32_e32 v112, v120, v113
	ds_bpermute_b32 v113, v150, v112
	v_cvt_pk_bf16_f32 v117, v114, v115
	v_lshl_add_u64 v[118:119], s[20:21], 0, v[154:155]
	v_mov_b32_e32 v170, v116
	v_mov_b32_e32 v171, v117
	s_nop 1
	v_permlane16_swap_b32_e32 v168, v170
	v_permlane16_swap_b32_e32 v169, v171
	global_store_dwordx4 v[166:167], v[168:171], off
	s_waitcnt lgkmcnt(0)
	v_add_f32_e32 v112, v112, v113
	ds_bpermute_b32 v113, v149, v112
	s_and_saveexec_b64 s[2:3], s[42:43]
	s_cbranch_execz .LBB0_673
	v_lshl_add_u64 v[114:115], v[144:145], 2, s[86:87]
	s_waitcnt lgkmcnt(0)
	v_add_f32_e32 v112, v112, v113
	global_atomic_add_f32 v[114:115], v112, off
; DI unsigned pk2(float a, float b) { f32x2 v = {a, b}; bf2_t r = __builtin_convertvector(v, bf2_t); return __builtin_bit_cast(unsigned, r); }
; __global__ void __launch_bounds__(512) hybrid_fwd(Params p) {
;     ...
;                   for (int m = 0; m < 4; ++m) { const int row = pm * 256 + ai * 128 + wr * 64 + m * 16 + fr; const size_t ro = (size_t)row * 1024 + pn * 256 + wc * 32 + 4 * fq;
;                       float ssq = 0.f;
; #pragma unroll
;                       for (int bj = 0; bj < 2; ++bj)
; #pragma unroll
;                           for (int n = 0; n < 2; ++n) { const size_t o = ro + bj * 128 + n * 16; const f32x4 v = *(const f32x4*)(X + o) + acc[ai][bj][m][n];
;                               u32x2 wv; wv[0] = pk2(v[0], v[1]); wv[1] = pk2(v[2], v[3]); *(u32x2*)(U + o) = wv;
;                               ssq += v[0] * v[0] + v[1] * v[1] + v[2] * v[2] + v[3] * v[3]; }
;                       ssq += __shfl_xor(ssq, 16); ssq += __shfl_xor(ssq, 32);
;                       if (fq == 0) unsafeAtomicAdd(SS1 + row, ssq); } }, vb); }
.LBB0_673:
	s_or_b64 exec, exec, s[2:3]
	v_or_b32_e32 v112, 16, v144
	s_waitcnt lgkmcnt(0)
	v_ashrrev_i32_e32 v113, 31, v112
	v_lshlrev_b64 v[114:115], 10, v[112:113]
	v_readlane_b32 s0, v246, 53
	v_lshl_add_u64 v[118:119], v[114:115], 0, v[142:143]
	v_readlane_b32 s1, v246, 54
	v_readlane_b32 s2, v246, 55
	v_readlane_b32 s3, v246, 56
	v_lshl_add_u64 v[120:121], v[118:119], 2, s[0:1]
	v_readlane_b32 s4, v246, 57
	v_readlane_b32 s5, v246, 58
	v_readlane_b32 s6, v246, 59
	v_readlane_b32 s7, v246, 60
	v_readlane_b32 s8, v246, 61
	v_readlane_b32 s9, v246, 62
	v_readlane_b32 s10, v246, 63
	v_readlane_b32 s11, v245, 0
	v_readlane_b32 s12, v245, 1
	v_readlane_b32 s13, v245, 2
	v_readlane_b32 s14, v245, 3
	v_readlane_b32 s15, v245, 4
	v_lshlrev_b64 v[116:117], 1, v[118:119]
	v_cvt_pk_bf16_f32 v114, v108, v109
	v_cvt_pk_bf16_f32 v115, v110, v111
	v_lshl_add_u64 v[118:119], s[20:21], 0, v[116:117]
	v_mov_b32_e32 v176, v114
	v_mov_b32_e32 v177, v115
	v_lshl_add_u64 v[184:185], v[118:119], 0, v[212:213]
	v_mul_f32_e32 v114, v109, v109
	v_fmac_f32_e32 v114, v108, v108
	v_fmac_f32_e32 v114, v110, v110
	v_fmac_f32_e32 v114, v111, v111
	s_nop 0
	v_cvt_pk_bf16_f32 v108, v104, v105
	v_mul_f32_e32 v105, v105, v105
	v_or_b32_e32 v110, 32, v116
	v_mov_b32_e32 v111, v117
	v_fmac_f32_e32 v105, v104, v104
	v_cvt_pk_bf16_f32 v109, v106, v107
	v_lshl_add_u64 v[110:111], s[20:21], 0, v[110:111]
	v_fmac_f32_e32 v105, v106, v106
	v_mov_b32_e32 v178, v108
	v_mov_b32_e32 v179, v109
	s_nop 1
	v_permlane16_swap_b32_e32 v176, v178
	v_permlane16_swap_b32_e32 v177, v179
	global_store_dwordx4 v[184:185], v[176:179], off
	v_fmac_f32_e32 v105, v107, v107
	v_add_f32_e32 v108, v114, v105
	s_nop 0
	v_cvt_pk_bf16_f32 v104, v100, v101
	v_mul_f32_e32 v101, v101, v101
	v_or_b32_e32 v106, 0x100, v116
	v_mov_b32_e32 v107, v117
	v_fmac_f32_e32 v101, v100, v100
	v_cvt_pk_bf16_f32 v105, v102, v103
	v_lshl_add_u64 v[106:107], s[20:21], 0, v[106:107]
	v_fmac_f32_e32 v101, v102, v102
	v_mov_b32_e32 v180, v104
	v_mov_b32_e32 v181, v105
	v_lshl_add_u64 v[186:187], v[106:107], 0, v[212:213]
	v_fmac_f32_e32 v101, v103, v103
	v_add_f32_e32 v104, v108, v101
	v_or_b32_e32 v116, 0x120, v116
	s_nop 0
	v_cvt_pk_bf16_f32 v100, v96, v97
	v_mul_f32_e32 v97, v97, v97
	v_fmac_f32_e32 v97, v96, v96
	v_fmac_f32_e32 v97, v98, v98
	v_fmac_f32_e32 v97, v99, v99
	v_add_f32_e32 v96, v104, v97
	ds_bpermute_b32 v97, v150, v96
	v_cvt_pk_bf16_f32 v101, v98, v99
	v_lshl_add_u64 v[102:103], s[20:21], 0, v[116:117]
	v_mov_b32_e32 v182, v100
	v_mov_b32_e32 v183, v101
	s_nop 1
	v_permlane16_swap_b32_e32 v180, v182
	v_permlane16_swap_b32_e32 v181, v183
	global_store_dwordx4 v[186:187], v[180:183], off
	s_waitcnt lgkmcnt(0)
	v_add_f32_e32 v96, v96, v97
	ds_bpermute_b32 v97, v149, v96
	s_and_saveexec_b64 s[2:3], s[42:43]
	s_cbranch_execz .LBB0_675
	v_lshl_add_u64 v[98:99], v[112:113], 2, s[86:87]
	s_waitcnt lgkmcnt(0)
	v_add_f32_e32 v96, v96, v97
	global_atomic_add_f32 v[98:99], v96, off
.LBB0_675:
	s_or_b64 exec, exec, s[2:3]
	v_or_b32_e32 v96, 32, v144
	s_waitcnt lgkmcnt(0)
	v_ashrrev_i32_e32 v97, 31, v96
	v_lshlrev_b64 v[98:99], 10, v[96:97]
	v_readlane_b32 s0, v246, 53
	v_lshl_add_u64 v[102:103], v[98:99], 0, v[142:143]
	v_readlane_b32 s1, v246, 54
	v_readlane_b32 s2, v246, 55
	v_readlane_b32 s3, v246, 56
	v_lshl_add_u64 v[104:105], v[102:103], 2, s[0:1]
	v_readlane_b32 s4, v246, 57
	v_readlane_b32 s5, v246, 58
	v_readlane_b32 s6, v246, 59
	v_readlane_b32 s7, v246, 60
	v_readlane_b32 s8, v246, 61
	v_readlane_b32 s9, v246, 62
	v_readlane_b32 s10, v246, 63
	v_readlane_b32 s11, v245, 0
	v_readlane_b32 s12, v245, 1
	v_readlane_b32 s13, v245, 2
	v_readlane_b32 s14, v245, 3
	v_readlane_b32 s15, v245, 4
	v_lshlrev_b64 v[100:101], 1, v[102:103]
	v_cvt_pk_bf16_f32 v98, v92, v93
	v_cvt_pk_bf16_f32 v99, v94, v95
	v_lshl_add_u64 v[102:103], s[20:21], 0, v[100:101]
	v_mov_b32_e32 v160, v98
	v_mov_b32_e32 v161, v99
	v_lshl_add_u64 v[164:165], v[102:103], 0, v[212:213]
	v_mul_f32_e32 v98, v93, v93
	v_fmac_f32_e32 v98, v92, v92
	v_fmac_f32_e32 v98, v94, v94
	v_fmac_f32_e32 v98, v95, v95
	s_nop 0
	v_cvt_pk_bf16_f32 v92, v88, v89
	v_mul_f32_e32 v89, v89, v89
	v_or_b32_e32 v94, 32, v100
	v_mov_b32_e32 v95, v101
	v_fmac_f32_e32 v89, v88, v88
	v_cvt_pk_bf16_f32 v93, v90, v91
	v_lshl_add_u64 v[94:95], s[20:21], 0, v[94:95]
	v_fmac_f32_e32 v89, v90, v90
	v_mov_b32_e32 v162, v92
	v_mov_b32_e32 v163, v93
	s_nop 1
	v_permlane16_swap_b32_e32 v160, v162
	v_permlane16_swap_b32_e32 v161, v163
	global_store_dwordx4 v[164:165], v[160:163], off
	v_fmac_f32_e32 v89, v91, v91
	v_add_f32_e32 v92, v98, v89
	s_nop 0
	v_cvt_pk_bf16_f32 v88, v84, v85
	v_mul_f32_e32 v85, v85, v85
	v_or_b32_e32 v90, 0x100, v100
	v_mov_b32_e32 v91, v101
	v_fmac_f32_e32 v85, v84, v84
	v_cvt_pk_bf16_f32 v89, v86, v87
	v_lshl_add_u64 v[90:91], s[20:21], 0, v[90:91]
	v_fmac_f32_e32 v85, v86, v86
	v_mov_b32_e32 v168, v88
	v_mov_b32_e32 v169, v89
	v_lshl_add_u64 v[166:167], v[90:91], 0, v[212:213]
	v_fmac_f32_e32 v85, v87, v87
	v_add_f32_e32 v88, v92, v85
	v_or_b32_e32 v100, 0x120, v100
	s_nop 0
	v_cvt_pk_bf16_f32 v84, v80, v81
	v_mul_f32_e32 v81, v81, v81
	v_fmac_f32_e32 v81, v80, v80
	v_fmac_f32_e32 v81, v82, v82
	v_fmac_f32_e32 v81, v83, v83
	v_add_f32_e32 v80, v88, v81
	ds_bpermute_b32 v81, v150, v80
	v_cvt_pk_bf16_f32 v85, v82, v83
	v_lshl_add_u64 v[86:87], s[20:21], 0, v[100:101]
	v_mov_b32_e32 v170, v84
	v_mov_b32_e32 v171, v85
	s_nop 1
	v_permlane16_swap_b32_e32 v168, v170
	v_permlane16_swap_b32_e32 v169, v171
	global_store_dwordx4 v[166:167], v[168:171], off
	s_waitcnt lgkmcnt(0)
	v_add_f32_e32 v80, v80, v81
	ds_bpermute_b32 v81, v149, v80
	s_and_saveexec_b64 s[2:3], s[42:43]
	s_cbranch_execz .LBB0_677
	v_lshl_add_u64 v[82:83], v[96:97], 2, s[86:87]
	s_waitcnt lgkmcnt(0)
	v_add_f32_e32 v80, v80, v81
	global_atomic_add_f32 v[82:83], v80, off
; DI unsigned pk2(float a, float b) { f32x2 v = {a, b}; bf2_t r = __builtin_convertvector(v, bf2_t); return __builtin_bit_cast(unsigned, r); }
; __global__ void __launch_bounds__(512) hybrid_fwd(Params p) {
;     ...
;                   for (int m = 0; m < 4; ++m) { const int row = pm * 256 + ai * 128 + wr * 64 + m * 16 + fr; const size_t ro = (size_t)row * 1024 + pn * 256 + wc * 32 + 4 * fq;
;                       float ssq = 0.f;
; #pragma unroll
;                       for (int bj = 0; bj < 2; ++bj)
; #pragma unroll
;                           for (int n = 0; n < 2; ++n) { const size_t o = ro + bj * 128 + n * 16; const f32x4 v = *(const f32x4*)(X + o) + acc[ai][bj][m][n];
;                               u32x2 wv; wv[0] = pk2(v[0], v[1]); wv[1] = pk2(v[2], v[3]); *(u32x2*)(U + o) = wv;
;                               ssq += v[0] * v[0] + v[1] * v[1] + v[2] * v[2] + v[3] * v[3]; }
;                       ssq += __shfl_xor(ssq, 16); ssq += __shfl_xor(ssq, 32);
;                       if (fq == 0) unsafeAtomicAdd(SS1 + row, ssq); } }, vb); }
.LBB0_677:
	s_or_b64 exec, exec, s[2:3]
	v_or_b32_e32 v80, 48, v144
	s_waitcnt lgkmcnt(0)
	v_ashrrev_i32_e32 v81, 31, v80
	v_lshlrev_b64 v[82:83], 10, v[80:81]
	v_readlane_b32 s0, v246, 53
	v_lshl_add_u64 v[86:87], v[82:83], 0, v[142:143]
	v_readlane_b32 s1, v246, 54
	v_readlane_b32 s2, v246, 55
	v_readlane_b32 s3, v246, 56
	v_lshl_add_u64 v[88:89], v[86:87], 2, s[0:1]
	v_readlane_b32 s4, v246, 57
	v_readlane_b32 s5, v246, 58
	v_readlane_b32 s6, v246, 59
	v_readlane_b32 s7, v246, 60
	v_readlane_b32 s8, v246, 61
	v_readlane_b32 s9, v246, 62
	v_readlane_b32 s10, v246, 63
	v_readlane_b32 s11, v245, 0
	v_readlane_b32 s12, v245, 1
	v_readlane_b32 s13, v245, 2
	v_readlane_b32 s14, v245, 3
	v_readlane_b32 s15, v245, 4
	v_lshlrev_b64 v[84:85], 1, v[86:87]
	v_cvt_pk_bf16_f32 v82, v76, v77
	v_cvt_pk_bf16_f32 v83, v78, v79
	v_lshl_add_u64 v[86:87], s[20:21], 0, v[84:85]
	v_mov_b32_e32 v176, v82
	v_mov_b32_e32 v177, v83
	v_lshl_add_u64 v[184:185], v[86:87], 0, v[212:213]
	v_mul_f32_e32 v82, v77, v77
	v_fmac_f32_e32 v82, v76, v76
	v_fmac_f32_e32 v82, v78, v78
	v_fmac_f32_e32 v82, v79, v79
	s_nop 0
	v_cvt_pk_bf16_f32 v76, v72, v73
	v_mul_f32_e32 v73, v73, v73
	v_or_b32_e32 v78, 32, v84
	v_mov_b32_e32 v79, v85
	v_fmac_f32_e32 v73, v72, v72
	v_cvt_pk_bf16_f32 v77, v74, v75
	v_lshl_add_u64 v[78:79], s[20:21], 0, v[78:79]
	v_fmac_f32_e32 v73, v74, v74
	v_mov_b32_e32 v178, v76
	v_mov_b32_e32 v179, v77
	s_nop 1
	v_permlane16_swap_b32_e32 v176, v178
	v_permlane16_swap_b32_e32 v177, v179
	global_store_dwordx4 v[184:185], v[176:179], off
	v_fmac_f32_e32 v73, v75, v75
	v_add_f32_e32 v76, v82, v73
	s_nop 0
	v_cvt_pk_bf16_f32 v72, v68, v69
	v_mul_f32_e32 v69, v69, v69
	v_or_b32_e32 v74, 0x100, v84
	v_mov_b32_e32 v75, v85
	v_fmac_f32_e32 v69, v68, v68
	v_cvt_pk_bf16_f32 v73, v70, v71
	v_lshl_add_u64 v[74:75], s[20:21], 0, v[74:75]
	v_fmac_f32_e32 v69, v70, v70
	v_mov_b32_e32 v180, v72
	v_mov_b32_e32 v181, v73
	v_lshl_add_u64 v[186:187], v[74:75], 0, v[212:213]
	v_fmac_f32_e32 v69, v71, v71
	v_add_f32_e32 v72, v76, v69
	v_or_b32_e32 v84, 0x120, v84
	s_nop 0
	v_cvt_pk_bf16_f32 v68, v64, v65
	v_mul_f32_e32 v65, v65, v65
	v_fmac_f32_e32 v65, v64, v64
	v_fmac_f32_e32 v65, v66, v66
	v_fmac_f32_e32 v65, v67, v67
	v_add_f32_e32 v64, v72, v65
	ds_bpermute_b32 v65, v150, v64
	v_cvt_pk_bf16_f32 v69, v66, v67
	v_lshl_add_u64 v[70:71], s[20:21], 0, v[84:85]
	v_mov_b32_e32 v182, v68
	v_mov_b32_e32 v183, v69
	s_nop 1
	v_permlane16_swap_b32_e32 v180, v182
	v_permlane16_swap_b32_e32 v181, v183
	global_store_dwordx4 v[186:187], v[180:183], off
	s_waitcnt lgkmcnt(0)
	v_add_f32_e32 v64, v64, v65
	ds_bpermute_b32 v65, v149, v64
	s_and_saveexec_b64 s[2:3], s[42:43]
	s_cbranch_execz .LBB0_679
	v_lshl_add_u64 v[66:67], v[80:81], 2, s[86:87]
	s_waitcnt lgkmcnt(0)
	v_add_f32_e32 v64, v64, v65
	global_atomic_add_f32 v[66:67], v64, off
.LBB0_679:
	s_or_b64 exec, exec, s[2:3]
	v_add_u32_e32 v64, 0x80, v144
	s_waitcnt lgkmcnt(0)
	v_ashrrev_i32_e32 v65, 31, v64
	v_lshlrev_b64 v[66:67], 10, v[64:65]
	v_readlane_b32 s0, v246, 53
	v_lshl_add_u64 v[70:71], v[66:67], 0, v[142:143]
	v_readlane_b32 s1, v246, 54
	v_readlane_b32 s2, v246, 55
	v_readlane_b32 s3, v246, 56
	v_lshl_add_u64 v[72:73], v[70:71], 2, s[0:1]
	v_readlane_b32 s4, v246, 57
	v_readlane_b32 s5, v246, 58
	v_readlane_b32 s6, v246, 59
	v_readlane_b32 s7, v246, 60
	v_readlane_b32 s8, v246, 61
	v_readlane_b32 s9, v246, 62
	v_readlane_b32 s10, v246, 63
	v_readlane_b32 s11, v245, 0
	v_readlane_b32 s12, v245, 1
	v_readlane_b32 s13, v245, 2
	v_readlane_b32 s14, v245, 3
	v_readlane_b32 s15, v245, 4
	v_lshlrev_b64 v[68:69], 1, v[70:71]
	v_cvt_pk_bf16_f32 v66, v60, v61
	v_cvt_pk_bf16_f32 v67, v62, v63
	v_lshl_add_u64 v[70:71], s[20:21], 0, v[68:69]
	v_mov_b32_e32 v160, v66
	v_mov_b32_e32 v161, v67
	v_lshl_add_u64 v[164:165], v[70:71], 0, v[212:213]
	v_mul_f32_e32 v66, v61, v61
	v_fmac_f32_e32 v66, v60, v60
	v_fmac_f32_e32 v66, v62, v62
	v_fmac_f32_e32 v66, v63, v63
	s_nop 0
	v_cvt_pk_bf16_f32 v60, v56, v57
	v_mul_f32_e32 v57, v57, v57
	v_or_b32_e32 v62, 32, v68
	v_mov_b32_e32 v63, v69
	v_fmac_f32_e32 v57, v56, v56
	v_cvt_pk_bf16_f32 v61, v58, v59
	v_lshl_add_u64 v[62:63], s[20:21], 0, v[62:63]
	v_fmac_f32_e32 v57, v58, v58
	v_mov_b32_e32 v162, v60
	v_mov_b32_e32 v163, v61
	s_nop 1
	v_permlane16_swap_b32_e32 v160, v162
	v_permlane16_swap_b32_e32 v161, v163
	global_store_dwordx4 v[164:165], v[160:163], off
	v_fmac_f32_e32 v57, v59, v59
	v_add_f32_e32 v60, v66, v57
	s_nop 0
	v_cvt_pk_bf16_f32 v56, v52, v53
	v_mul_f32_e32 v53, v53, v53
	v_or_b32_e32 v58, 0x100, v68
	v_mov_b32_e32 v59, v69
	v_fmac_f32_e32 v53, v52, v52
	v_cvt_pk_bf16_f32 v57, v54, v55
	v_lshl_add_u64 v[58:59], s[20:21], 0, v[58:59]
	v_fmac_f32_e32 v53, v54, v54
	v_mov_b32_e32 v168, v56
	v_mov_b32_e32 v169, v57
	v_lshl_add_u64 v[166:167], v[58:59], 0, v[212:213]
	v_fmac_f32_e32 v53, v55, v55
	v_add_f32_e32 v56, v60, v53
	v_or_b32_e32 v68, 0x120, v68
	s_nop 0
	v_cvt_pk_bf16_f32 v52, v48, v49
	v_mul_f32_e32 v49, v49, v49
	v_fmac_f32_e32 v49, v48, v48
	v_fmac_f32_e32 v49, v50, v50
	v_fmac_f32_e32 v49, v51, v51
	v_add_f32_e32 v48, v56, v49
	ds_bpermute_b32 v49, v150, v48
	v_cvt_pk_bf16_f32 v53, v50, v51
	v_lshl_add_u64 v[54:55], s[20:21], 0, v[68:69]
	v_mov_b32_e32 v170, v52
	v_mov_b32_e32 v171, v53
	s_nop 1
	v_permlane16_swap_b32_e32 v168, v170
	v_permlane16_swap_b32_e32 v169, v171
	global_store_dwordx4 v[166:167], v[168:171], off
	s_waitcnt lgkmcnt(0)
	v_add_f32_e32 v48, v48, v49
	ds_bpermute_b32 v49, v149, v48
	s_and_saveexec_b64 s[2:3], s[42:43]
	s_cbranch_execz .LBB0_681
	v_lshl_add_u64 v[50:51], v[64:65], 2, s[86:87]
	s_waitcnt lgkmcnt(0)
	v_add_f32_e32 v48, v48, v49
	global_atomic_add_f32 v[50:51], v48, off
; DI unsigned pk2(float a, float b) { f32x2 v = {a, b}; bf2_t r = __builtin_convertvector(v, bf2_t); return __builtin_bit_cast(unsigned, r); }
; __global__ void __launch_bounds__(512) hybrid_fwd(Params p) {
;     ...
;                   for (int m = 0; m < 4; ++m) { const int row = pm * 256 + ai * 128 + wr * 64 + m * 16 + fr; const size_t ro = (size_t)row * 1024 + pn * 256 + wc * 32 + 4 * fq;
;                       float ssq = 0.f;
; #pragma unroll
;                       for (int bj = 0; bj < 2; ++bj)
; #pragma unroll
;                           for (int n = 0; n < 2; ++n) { const size_t o = ro + bj * 128 + n * 16; const f32x4 v = *(const f32x4*)(X + o) + acc[ai][bj][m][n];
;                               u32x2 wv; wv[0] = pk2(v[0], v[1]); wv[1] = pk2(v[2], v[3]); *(u32x2*)(U + o) = wv;
;                               ssq += v[0] * v[0] + v[1] * v[1] + v[2] * v[2] + v[3] * v[3]; }
;                       ssq += __shfl_xor(ssq, 16); ssq += __shfl_xor(ssq, 32);
;                       if (fq == 0) unsafeAtomicAdd(SS1 + row, ssq); } }, vb); }
.LBB0_681:
	s_or_b64 exec, exec, s[2:3]
	v_add_u32_e32 v48, 0x90, v144
	s_waitcnt lgkmcnt(0)
	v_ashrrev_i32_e32 v49, 31, v48
	v_lshlrev_b64 v[50:51], 10, v[48:49]
	v_readlane_b32 s0, v246, 53
	v_lshl_add_u64 v[54:55], v[50:51], 0, v[142:143]
	v_readlane_b32 s1, v246, 54
	v_readlane_b32 s2, v246, 55
	v_readlane_b32 s3, v246, 56
	v_lshl_add_u64 v[56:57], v[54:55], 2, s[0:1]
	v_readlane_b32 s4, v246, 57
	v_readlane_b32 s5, v246, 58
	v_readlane_b32 s6, v246, 59
	v_readlane_b32 s7, v246, 60
	v_readlane_b32 s8, v246, 61
	v_readlane_b32 s9, v246, 62
	v_readlane_b32 s10, v246, 63
	v_readlane_b32 s11, v245, 0
	v_readlane_b32 s12, v245, 1
	v_readlane_b32 s13, v245, 2
	v_readlane_b32 s14, v245, 3
	v_readlane_b32 s15, v245, 4
	v_lshlrev_b64 v[52:53], 1, v[54:55]
	v_cvt_pk_bf16_f32 v50, v44, v45
	v_cvt_pk_bf16_f32 v51, v46, v47
	v_lshl_add_u64 v[54:55], s[20:21], 0, v[52:53]
	v_mov_b32_e32 v176, v50
	v_mov_b32_e32 v177, v51
	v_lshl_add_u64 v[184:185], v[54:55], 0, v[212:213]
	v_mul_f32_e32 v50, v45, v45
	v_fmac_f32_e32 v50, v44, v44
	v_fmac_f32_e32 v50, v46, v46
	v_fmac_f32_e32 v50, v47, v47
	s_nop 0
	v_cvt_pk_bf16_f32 v44, v40, v41
	v_mul_f32_e32 v41, v41, v41
	v_or_b32_e32 v46, 32, v52
	v_mov_b32_e32 v47, v53
	v_fmac_f32_e32 v41, v40, v40
	v_cvt_pk_bf16_f32 v45, v42, v43
	v_lshl_add_u64 v[46:47], s[20:21], 0, v[46:47]
	v_fmac_f32_e32 v41, v42, v42
	v_mov_b32_e32 v178, v44
	v_mov_b32_e32 v179, v45
	s_nop 1
	v_permlane16_swap_b32_e32 v176, v178
	v_permlane16_swap_b32_e32 v177, v179
	global_store_dwordx4 v[184:185], v[176:179], off
	v_fmac_f32_e32 v41, v43, v43
	v_add_f32_e32 v44, v50, v41
	s_nop 0
	v_cvt_pk_bf16_f32 v40, v36, v37
	v_mul_f32_e32 v37, v37, v37
	v_or_b32_e32 v42, 0x100, v52
	v_mov_b32_e32 v43, v53
	v_fmac_f32_e32 v37, v36, v36
	v_cvt_pk_bf16_f32 v41, v38, v39
	v_lshl_add_u64 v[42:43], s[20:21], 0, v[42:43]
	v_fmac_f32_e32 v37, v38, v38
	v_mov_b32_e32 v180, v40
	v_mov_b32_e32 v181, v41
	v_lshl_add_u64 v[186:187], v[42:43], 0, v[212:213]
	v_fmac_f32_e32 v37, v39, v39
	v_add_f32_e32 v40, v44, v37
	v_or_b32_e32 v52, 0x120, v52
	s_nop 0
	v_cvt_pk_bf16_f32 v36, v32, v33
	v_mul_f32_e32 v33, v33, v33
	v_fmac_f32_e32 v33, v32, v32
	v_fmac_f32_e32 v33, v34, v34
	v_fmac_f32_e32 v33, v35, v35
	v_add_f32_e32 v32, v40, v33
	ds_bpermute_b32 v33, v150, v32
	v_cvt_pk_bf16_f32 v37, v34, v35
	v_lshl_add_u64 v[38:39], s[20:21], 0, v[52:53]
	v_mov_b32_e32 v182, v36
	v_mov_b32_e32 v183, v37
	s_nop 1
	v_permlane16_swap_b32_e32 v180, v182
	v_permlane16_swap_b32_e32 v181, v183
	global_store_dwordx4 v[186:187], v[180:183], off
	s_waitcnt lgkmcnt(0)
	v_add_f32_e32 v32, v32, v33
	ds_bpermute_b32 v33, v149, v32
	s_and_saveexec_b64 s[2:3], s[42:43]
	s_cbranch_execz .LBB0_683
	v_lshl_add_u64 v[34:35], v[48:49], 2, s[86:87]
	s_waitcnt lgkmcnt(0)
	v_add_f32_e32 v32, v32, v33
	global_atomic_add_f32 v[34:35], v32, off
; DI unsigned pk2(float a, float b) { f32x2 v = {a, b}; bf2_t r = __builtin_convertvector(v, bf2_t); return __builtin_bit_cast(unsigned, r); }
; __global__ void __launch_bounds__(512) hybrid_fwd(Params p) {
;     ...
;                   for (int m = 0; m < 4; ++m) { const int row = pm * 256 + ai * 128 + wr * 64 + m * 16 + fr; const size_t ro = (size_t)row * 1024 + pn * 256 + wc * 32 + 4 * fq;
;                       float ssq = 0.f;
; #pragma unroll
;                       for (int bj = 0; bj < 2; ++bj)
; #pragma unroll
;                           for (int n = 0; n < 2; ++n) { const size_t o = ro + bj * 128 + n * 16; const f32x4 v = *(const f32x4*)(X + o) + acc[ai][bj][m][n];
;                               u32x2 wv; wv[0] = pk2(v[0], v[1]); wv[1] = pk2(v[2], v[3]); *(u32x2*)(U + o) = wv;
;                               ssq += v[0] * v[0] + v[1] * v[1] + v[2] * v[2] + v[3] * v[3]; }
;                       ssq += __shfl_xor(ssq, 16); ssq += __shfl_xor(ssq, 32);
;                       if (fq == 0) unsafeAtomicAdd(SS1 + row, ssq); } }, vb); }
.LBB0_683:
	s_or_b64 exec, exec, s[2:3]
	v_add_u32_e32 v32, 0xa0, v144
	s_waitcnt lgkmcnt(0)
	v_ashrrev_i32_e32 v33, 31, v32
	v_lshlrev_b64 v[34:35], 10, v[32:33]
	v_readlane_b32 s0, v246, 53
	v_lshl_add_u64 v[38:39], v[34:35], 0, v[142:143]
	v_readlane_b32 s1, v246, 54
	v_readlane_b32 s2, v246, 55
	v_readlane_b32 s3, v246, 56
	v_lshl_add_u64 v[40:41], v[38:39], 2, s[0:1]
	v_readlane_b32 s4, v246, 57
	v_readlane_b32 s5, v246, 58
	v_readlane_b32 s6, v246, 59
	v_readlane_b32 s7, v246, 60
	v_readlane_b32 s8, v246, 61
	v_readlane_b32 s9, v246, 62
	v_readlane_b32 s10, v246, 63
	v_readlane_b32 s11, v245, 0
	v_readlane_b32 s12, v245, 1
	v_readlane_b32 s13, v245, 2
	v_readlane_b32 s14, v245, 3
	v_readlane_b32 s15, v245, 4
	v_lshlrev_b64 v[36:37], 1, v[38:39]
	v_cvt_pk_bf16_f32 v34, v28, v29
	v_cvt_pk_bf16_f32 v35, v30, v31
	v_lshl_add_u64 v[38:39], s[20:21], 0, v[36:37]
	v_mov_b32_e32 v160, v34
	v_mov_b32_e32 v161, v35
	v_lshl_add_u64 v[164:165], v[38:39], 0, v[212:213]
	v_mul_f32_e32 v34, v29, v29
	v_fmac_f32_e32 v34, v28, v28
	v_fmac_f32_e32 v34, v30, v30
	v_fmac_f32_e32 v34, v31, v31
	s_nop 0
	v_cvt_pk_bf16_f32 v28, v24, v25
	v_mul_f32_e32 v25, v25, v25
	v_or_b32_e32 v30, 32, v36
	v_mov_b32_e32 v31, v37
	v_fmac_f32_e32 v25, v24, v24
	v_cvt_pk_bf16_f32 v29, v26, v27
	v_lshl_add_u64 v[30:31], s[20:21], 0, v[30:31]
	v_fmac_f32_e32 v25, v26, v26
	v_mov_b32_e32 v162, v28
	v_mov_b32_e32 v163, v29
	s_nop 1
	v_permlane16_swap_b32_e32 v160, v162
	v_permlane16_swap_b32_e32 v161, v163
	global_store_dwordx4 v[164:165], v[160:163], off
	v_fmac_f32_e32 v25, v27, v27
	v_add_f32_e32 v28, v34, v25
	s_nop 0
	v_cvt_pk_bf16_f32 v24, v20, v21
	v_mul_f32_e32 v21, v21, v21
	v_or_b32_e32 v26, 0x100, v36
	v_mov_b32_e32 v27, v37
	v_fmac_f32_e32 v21, v20, v20
	v_cvt_pk_bf16_f32 v25, v22, v23
	v_lshl_add_u64 v[26:27], s[20:21], 0, v[26:27]
	v_fmac_f32_e32 v21, v22, v22
	v_mov_b32_e32 v168, v24
	v_mov_b32_e32 v169, v25
	v_lshl_add_u64 v[166:167], v[26:27], 0, v[212:213]
	v_fmac_f32_e32 v21, v23, v23
	v_add_f32_e32 v24, v28, v21
	v_or_b32_e32 v36, 0x120, v36
	s_nop 0
	v_cvt_pk_bf16_f32 v20, v16, v17
	v_mul_f32_e32 v17, v17, v17
	v_fmac_f32_e32 v17, v16, v16
	v_fmac_f32_e32 v17, v18, v18
	v_fmac_f32_e32 v17, v19, v19
	v_add_f32_e32 v16, v24, v17
	ds_bpermute_b32 v17, v150, v16
	v_cvt_pk_bf16_f32 v21, v18, v19
	v_lshl_add_u64 v[22:23], s[20:21], 0, v[36:37]
	v_mov_b32_e32 v170, v20
	v_mov_b32_e32 v171, v21
	s_nop 1
	v_permlane16_swap_b32_e32 v168, v170
	v_permlane16_swap_b32_e32 v169, v171
	global_store_dwordx4 v[166:167], v[168:171], off
	s_waitcnt lgkmcnt(0)
	v_add_f32_e32 v16, v16, v17
	ds_bpermute_b32 v17, v149, v16
	s_and_saveexec_b64 s[2:3], s[42:43]
	s_cbranch_execz .LBB0_685
	v_lshl_add_u64 v[18:19], v[32:33], 2, s[86:87]
	s_waitcnt lgkmcnt(0)
	v_add_f32_e32 v16, v16, v17
	global_atomic_add_f32 v[18:19], v16, off
.LBB0_685:
	s_or_b64 exec, exec, s[2:3]
	v_add_u32_e32 v16, 0xb0, v144
	s_waitcnt lgkmcnt(0)
	v_ashrrev_i32_e32 v17, 31, v16
	v_lshlrev_b64 v[18:19], 10, v[16:17]
	v_readlane_b32 s0, v246, 53
	v_lshl_add_u64 v[22:23], v[18:19], 0, v[142:143]
	v_readlane_b32 s1, v246, 54
	v_readlane_b32 s2, v246, 55
	v_readlane_b32 s3, v246, 56
	v_lshl_add_u64 v[24:25], v[22:23], 2, s[0:1]
	v_readlane_b32 s4, v246, 57
	v_readlane_b32 s5, v246, 58
	v_readlane_b32 s6, v246, 59
	v_readlane_b32 s7, v246, 60
	v_readlane_b32 s8, v246, 61
	v_readlane_b32 s9, v246, 62
	v_readlane_b32 s10, v246, 63
	v_readlane_b32 s11, v245, 0
	v_readlane_b32 s12, v245, 1
	v_readlane_b32 s13, v245, 2
	v_readlane_b32 s14, v245, 3
	v_readlane_b32 s15, v245, 4
	v_lshlrev_b64 v[20:21], 1, v[22:23]
	v_cvt_pk_bf16_f32 v18, v12, v13
	v_cvt_pk_bf16_f32 v19, v14, v15
	v_lshl_add_u64 v[22:23], s[20:21], 0, v[20:21]
	v_mov_b32_e32 v176, v18
	v_mov_b32_e32 v177, v19
	v_lshl_add_u64 v[184:185], v[22:23], 0, v[212:213]
	v_mul_f32_e32 v18, v13, v13
	v_fmac_f32_e32 v18, v12, v12
	v_fmac_f32_e32 v18, v14, v14
	v_fmac_f32_e32 v18, v15, v15
	s_nop 0
	v_cvt_pk_bf16_f32 v12, v8, v9
	v_mul_f32_e32 v9, v9, v9
	v_or_b32_e32 v14, 32, v20
	v_mov_b32_e32 v15, v21
	v_fmac_f32_e32 v9, v8, v8
	v_cvt_pk_bf16_f32 v13, v10, v11
	v_lshl_add_u64 v[14:15], s[20:21], 0, v[14:15]
	v_fmac_f32_e32 v9, v10, v10
	v_mov_b32_e32 v178, v12
	v_mov_b32_e32 v179, v13
	s_nop 1
	v_permlane16_swap_b32_e32 v176, v178
	v_permlane16_swap_b32_e32 v177, v179
	global_store_dwordx4 v[184:185], v[176:179], off
	v_fmac_f32_e32 v9, v11, v11
	v_add_f32_e32 v12, v18, v9
	s_nop 0
	v_cvt_pk_bf16_f32 v8, v4, v5
	v_mul_f32_e32 v5, v5, v5
	v_or_b32_e32 v10, 0x100, v20
	v_mov_b32_e32 v11, v21
	v_fmac_f32_e32 v5, v4, v4
	v_cvt_pk_bf16_f32 v9, v6, v7
	v_lshl_add_u64 v[10:11], s[20:21], 0, v[10:11]
	v_fmac_f32_e32 v5, v6, v6
	v_mov_b32_e32 v180, v8
	v_mov_b32_e32 v181, v9
	v_lshl_add_u64 v[186:187], v[10:11], 0, v[212:213]
	v_fmac_f32_e32 v5, v7, v7
	v_add_f32_e32 v8, v12, v5
	v_or_b32_e32 v20, 0x120, v20
	s_nop 0
	v_cvt_pk_bf16_f32 v4, v0, v1
	v_mul_f32_e32 v1, v1, v1
	v_fmac_f32_e32 v1, v0, v0
	v_fmac_f32_e32 v1, v2, v2
	v_fmac_f32_e32 v1, v3, v3
	v_add_f32_e32 v0, v8, v1
	ds_bpermute_b32 v1, v150, v0
	v_cvt_pk_bf16_f32 v5, v2, v3
	v_lshl_add_u64 v[6:7], s[20:21], 0, v[20:21]
	v_mov_b32_e32 v182, v4
	v_mov_b32_e32 v183, v5
	s_nop 1
	v_permlane16_swap_b32_e32 v180, v182
	v_permlane16_swap_b32_e32 v181, v183
	global_store_dwordx4 v[186:187], v[180:183], off
	s_waitcnt lgkmcnt(0)
	v_add_f32_e32 v0, v0, v1
	ds_bpermute_b32 v1, v149, v0
	s_and_saveexec_b64 s[2:3], s[42:43]
	s_cbranch_execz .LBB0_666
	v_lshl_add_u64 v[2:3], v[16:17], 2, s[86:87]
	s_waitcnt lgkmcnt(0)
	v_add_f32_e32 v0, v0, v1
	global_atomic_add_f32 v[2:3], v0, off
	s_branch .LBB0_666

; #define G_STAGE(bufoff, gbase, voff) do { _Pragma("unroll") for (int _i = 0; _i < 2; ++_i) \
;         __builtin_amdgcn_global_load_lds((const unsigned*)((const char*)(gbase) + (voff)[_i]), (LAS unsigned*)(lds + (bufoff) + ldsw + _i * 8192), 16, 0, 0); } while (0)
; #define G_LDA(dst, b, h) do { _Pragma("unroll") for (int m = 0; m < 4; ++m) _Pragma("unroll") for (int k = 0; k < 2; ++k) dst[m][k] = *(const LAS bf16x8*)(lds + G_SA(b, h) + aoff + m * 2048 + k * 1024); } while (0)
; #define G_LDB(dst, b, h) do { _Pragma("unroll") for (int n = 0; n < 2; ++n) _Pragma("unroll") for (int k = 0; k < 2; ++k) dst[n][k] = *(const LAS bf16x8*)(lds + G_SB(b, h) + boff + n * 2048 + k * 1024); } while (0)
; #define G_MMA(ai, bj, At, Bt) do { __builtin_amdgcn_s_setprio(1); _Pragma("unroll") for (int m = 0; m < 4; ++m) _Pragma("unroll") for (int n = 0; n < 2; ++n) _Pragma("unroll") for (int k = 0; k < 2; ++k) \
;         acc[ai][bj][m][n] = __builtin_amdgcn_mfma_f32_16x16x32_bf16(Bt[n][k], At[m][k], acc[ai][bj][m][n], 0, 0, 0); __builtin_amdgcn_s_setprio(0); } while (0)
; #define G_WAIT_V(n) asm volatile("s_waitcnt vmcnt(" #n ")" ::: "memory")
; #define G_WAIT_L(n) asm volatile("s_waitcnt lgkmcnt(" #n ")" ::: "memory")
; template <bool PERM, class Dec, class Epi>
; DI void gemm_phase(LAS unsigned char* lds, const int nM, const int nN, const int K, const int lda, const int ldb, const Dec& dec, const Epi& epi, const int vb, const int panel = -1) {
;     ...
;         for (int t = 0; t < nt; t += 2) {
;             const bool last = (t == nt - 2);
;             const char* a1 = cA + (size_t)(t + 1) * kstep;
;             const char* a2 = last ? nA : cA + (size_t)(t + 2) * kstep; const char* b2 = last ? nB : cB + (size_t)(t + 2) * kstep;
;             const char* a3 = a2 + kstep; const char* b3 = b2 + kstep;
;             G_LDB(B0, 0, 0); G_SCHED; G_LDA(At, 0, 0); G_STAGE(G_SA(1, 1), a1 + hstepA, voffA);
;             G_WAIT_L(8); G_BAR; G_WAIT_L(0); G_MMA(0, 0, At, B0); G_BAR; G_SCHED;
;             G_LDB(B1, 0, 1); G_STAGE(G_SB(0, 0), b2, voffB);
;             G_BAR; G_WAIT_L(0); G_MMA(0, 1, At, B1); G_BAR;
;             G_LDA(At, 0, 1); G_STAGE(G_SA(0, 0), a2, voffA);
;             G_BAR; G_WAIT_L(0); G_MMA(1, 0, At, B0); G_BAR; G_SCHED;
;             G_STAGE(G_SB(0, 1), b2 + hstepB, voffB);
;             G_WAIT_V(6); G_BAR; G_MMA(1, 1, At, B1); G_BAR;
.LBB0_924:
	s_add_u32 s22, s18, 0x100
	s_addc_u32 s23, s19, 0
	s_add_i32 s53, 0, 0x10000
	v_add_u32_e32 v140, s53, v144
	ds_read_b128 v[162:165], v140
	ds_read_b128 v[166:169], v140 offset:1024
	ds_read_b128 v[170:173], v140 offset:2048
	ds_read_b128 v[176:179], v140 offset:3072
	s_cmp_eq_u32 s52, 20
	s_cselect_b32 s29, s13, s23
	s_cselect_b32 s28, s12, s22
	s_cselect_b32 s25, s17, s51
	s_cselect_b32 s24, s16, s50
	v_lshl_add_u64 v[140:141], s[18:19], 0, v[136:137]
	s_add_i32 m0, s39, 0xc000
	ds_read_b128 v[180:183], v160
	ds_read_b128 v[184:187], v160 offset:1024
	ds_read_b128 v[188:191], v160 offset:2048
	ds_read_b128 v[194:197], v160 offset:3072
	ds_read_b128 v[198:201], v160 offset:4096
	ds_read_b128 v[202:205], v160 offset:5120
	ds_read_b128 v[206:209], v160 offset:6144
	ds_read_b128 v[210:213], v160 offset:7168
	global_load_lds_dwordx4 v[140:141], off
	v_lshl_add_u64 v[140:141], s[18:19], 0, v[138:139]
	s_add_i32 m0, s39, 0xe000
	s_nop 0
	global_load_lds_dwordx4 v[140:141], off
	s_waitcnt lgkmcnt(8)
	s_barrier
	s_waitcnt lgkmcnt(0)
	s_setprio 1
	s_waitcnt lgkmcnt(0)
	v_mfma_f32_16x16x32_bf16 v[124:127], v[162:165], v[180:183], v[124:127]
	v_mfma_f32_16x16x32_bf16 v[120:123], v[170:173], v[180:183], v[120:123]
	v_mfma_f32_16x16x32_bf16 v[108:111], v[162:165], v[188:191], v[108:111]
	v_mfma_f32_16x16x32_bf16 v[104:107], v[170:173], v[188:191], v[104:107]
	v_mfma_f32_16x16x32_bf16 v[92:95], v[162:165], v[198:201], v[92:95]
	v_mfma_f32_16x16x32_bf16 v[88:91], v[170:173], v[198:201], v[88:91]
	v_mfma_f32_16x16x32_bf16 v[76:79], v[162:165], v[206:209], v[76:79]
	v_mfma_f32_16x16x32_bf16 v[72:75], v[170:173], v[206:209], v[72:75]
	v_mfma_f32_16x16x32_bf16 v[124:127], v[166:169], v[184:187], v[124:127]
	v_mfma_f32_16x16x32_bf16 v[120:123], v[176:179], v[184:187], v[120:123]
	v_mfma_f32_16x16x32_bf16 v[108:111], v[166:169], v[194:197], v[108:111]
	v_mfma_f32_16x16x32_bf16 v[104:107], v[176:179], v[194:197], v[104:107]
	v_mfma_f32_16x16x32_bf16 v[92:95], v[166:169], v[202:205], v[92:95]
	v_mfma_f32_16x16x32_bf16 v[88:91], v[176:179], v[202:205], v[88:91]
	v_mfma_f32_16x16x32_bf16 v[76:79], v[166:169], v[210:213], v[76:79]
	v_mfma_f32_16x16x32_bf16 v[72:75], v[176:179], v[210:213], v[72:75]
	s_setprio 0
	s_barrier
	s_add_i32 s54, 0, 0x14000
	v_add_u32_e32 v140, s54, v144
	s_add_i32 s18, s53, s38
	ds_read_b128 v[214:217], v140
	ds_read_b128 v[218:221], v140 offset:1024
	ds_read_b128 v[222:225], v140 offset:2048
	ds_read_b128 v[226:229], v140 offset:3072
	v_lshl_add_u64 v[140:141], s[24:25], 0, v[128:129]
	s_mov_b32 m0, s18
	v_lshl_add_u64 v[230:231], s[24:25], 0, v[132:133]
	global_load_lds_dwordx4 v[140:141], off
	s_add_i32 m0, s18, 0x2000
	s_nop 0
	global_load_lds_dwordx4 v[230:231], off
	s_barrier
	s_waitcnt lgkmcnt(0)
	s_setprio 1
	s_waitcnt lgkmcnt(0)
	v_mfma_f32_16x16x32_bf16 v[116:119], v[214:217], v[180:183], v[116:119]
	v_mfma_f32_16x16x32_bf16 v[112:115], v[222:225], v[180:183], v[112:115]
	v_mfma_f32_16x16x32_bf16 v[100:103], v[214:217], v[188:191], v[100:103]
	v_mfma_f32_16x16x32_bf16 v[96:99], v[222:225], v[188:191], v[96:99]
	v_mfma_f32_16x16x32_bf16 v[84:87], v[214:217], v[198:201], v[84:87]
	v_mfma_f32_16x16x32_bf16 v[80:83], v[222:225], v[198:201], v[80:83]
	v_mfma_f32_16x16x32_bf16 v[68:71], v[214:217], v[206:209], v[68:71]
	v_mfma_f32_16x16x32_bf16 v[64:67], v[222:225], v[206:209], v[64:67]
	v_mfma_f32_16x16x32_bf16 v[116:119], v[218:221], v[184:187], v[116:119]
	v_mfma_f32_16x16x32_bf16 v[112:115], v[226:229], v[184:187], v[112:115]
	v_mfma_f32_16x16x32_bf16 v[100:103], v[218:221], v[194:197], v[100:103]
	v_mfma_f32_16x16x32_bf16 v[96:99], v[226:229], v[194:197], v[96:99]
	v_mfma_f32_16x16x32_bf16 v[84:87], v[218:221], v[202:205], v[84:87]
	v_mfma_f32_16x16x32_bf16 v[80:83], v[226:229], v[202:205], v[80:83]
	v_mfma_f32_16x16x32_bf16 v[68:71], v[218:221], v[210:213], v[68:71]
	v_mfma_f32_16x16x32_bf16 v[64:67], v[226:229], v[210:213], v[64:67]
	s_setprio 0
	s_mov_b32 m0, s39
	v_lshl_add_u64 v[232:233], s[28:29], 0, v[128:129]
	s_barrier
	ds_read_b128 v[180:183], v160 offset:16384
	ds_read_b128 v[184:187], v160 offset:17408
	ds_read_b128 v[188:191], v160 offset:18432
	ds_read_b128 v[194:197], v160 offset:19456
	ds_read_b128 v[198:201], v160 offset:20480
	ds_read_b128 v[202:205], v160 offset:21504
	ds_read_b128 v[206:209], v160 offset:22528
	ds_read_b128 v[210:213], v160 offset:23552
	global_load_lds_dwordx4 v[232:233], off
	v_lshl_add_u64 v[234:235], s[28:29], 0, v[132:133]
	s_mov_b32 m0, s40
	s_nop 0
	global_load_lds_dwordx4 v[234:235], off
	s_barrier
	s_waitcnt lgkmcnt(0)
	s_setprio 1
	s_waitcnt lgkmcnt(0)
	v_mfma_f32_16x16x32_bf16 v[60:63], v[162:165], v[180:183], v[60:63]
	v_mfma_f32_16x16x32_bf16 v[56:59], v[170:173], v[180:183], v[56:59]
	v_mfma_f32_16x16x32_bf16 v[44:47], v[162:165], v[188:191], v[44:47]
	v_mfma_f32_16x16x32_bf16 v[40:43], v[170:173], v[188:191], v[40:43]
	v_mfma_f32_16x16x32_bf16 v[28:31], v[162:165], v[198:201], v[28:31]
	v_mfma_f32_16x16x32_bf16 v[24:27], v[170:173], v[198:201], v[24:27]
	v_mfma_f32_16x16x32_bf16 v[12:15], v[162:165], v[206:209], v[12:15]
	v_mfma_f32_16x16x32_bf16 v[8:11], v[170:173], v[206:209], v[8:11]
	v_mfma_f32_16x16x32_bf16 v[60:63], v[166:169], v[184:187], v[60:63]
	v_mfma_f32_16x16x32_bf16 v[56:59], v[176:179], v[184:187], v[56:59]
	v_mfma_f32_16x16x32_bf16 v[44:47], v[166:169], v[194:197], v[44:47]
	v_mfma_f32_16x16x32_bf16 v[40:43], v[176:179], v[194:197], v[40:43]
	v_mfma_f32_16x16x32_bf16 v[28:31], v[166:169], v[202:205], v[28:31]
	v_mfma_f32_16x16x32_bf16 v[24:27], v[176:179], v[202:205], v[24:27]
	v_mfma_f32_16x16x32_bf16 v[12:15], v[166:169], v[210:213], v[12:15]
	v_mfma_f32_16x16x32_bf16 v[8:11], v[176:179], v[210:213], v[8:11]
	s_setprio 0
	s_barrier
; #define G_STAGE(bufoff, gbase, voff) do { _Pragma("unroll") for (int _i = 0; _i < 2; ++_i) \
;         __builtin_amdgcn_global_load_lds((const unsigned*)((const char*)(gbase) + (voff)[_i]), (LAS unsigned*)(lds + (bufoff) + ldsw + _i * 8192), 16, 0, 0); } while (0)
; #define G_LDA(dst, b, h) do { _Pragma("unroll") for (int m = 0; m < 4; ++m) _Pragma("unroll") for (int k = 0; k < 2; ++k) dst[m][k] = *(const LAS bf16x8*)(lds + G_SA(b, h) + aoff + m * 2048 + k * 1024); } while (0)
; #define G_LDB(dst, b, h) do { _Pragma("unroll") for (int n = 0; n < 2; ++n) _Pragma("unroll") for (int k = 0; k < 2; ++k) dst[n][k] = *(const LAS bf16x8*)(lds + G_SB(b, h) + boff + n * 2048 + k * 1024); } while (0)
; #define G_MMA(ai, bj, At, Bt) do { __builtin_amdgcn_s_setprio(1); _Pragma("unroll") for (int m = 0; m < 4; ++m) _Pragma("unroll") for (int n = 0; n < 2; ++n) _Pragma("unroll") for (int k = 0; k < 2; ++k) \
;         acc[ai][bj][m][n] = __builtin_amdgcn_mfma_f32_16x16x32_bf16(Bt[n][k], At[m][k], acc[ai][bj][m][n], 0, 0, 0); __builtin_amdgcn_s_setprio(0); } while (0)
; #define G_WAIT_V(n) asm volatile("s_waitcnt vmcnt(" #n ")" ::: "memory")
; #define G_WAIT_L(n) asm volatile("s_waitcnt lgkmcnt(" #n ")" ::: "memory")
; #define G_BAR __builtin_amdgcn_s_barrier()
; #define G_SCHED __builtin_amdgcn_sched_barrier(0)
; template <bool PERM, class Dec, class Epi>
; DI void gemm_phase(LAS unsigned char* lds, const int nM, const int nN, const int K, const int lda, const int ldb, const Dec& dec, const Epi& epi, const int vb, const int panel = -1) {
;     ...
;             G_STAGE(G_SB(0, 1), b2 + hstepB, voffB);
;             G_WAIT_V(6); G_BAR; G_MMA(1, 1, At, B1); G_BAR;
;             G_LDB(B0, 1, 0); G_SCHED; G_LDA(At, 1, 0); G_STAGE(G_SA(0, 1), a2 + hstepA, voffA);
;             G_WAIT_L(8); G_BAR; G_WAIT_L(0); G_MMA(0, 0, At, B0); G_BAR; G_SCHED;
;             G_LDB(B1, 1, 1); G_STAGE(G_SB(1, 0), b3, voffB);
;             G_BAR; G_WAIT_L(0); G_MMA(0, 1, At, B1); G_BAR;
;             G_LDA(At, 1, 1); G_STAGE(G_SA(1, 0), a3, voffA);
;             G_BAR; G_WAIT_L(0); G_MMA(1, 0, At, B0); G_BAR; G_SCHED;
	s_add_u32 s18, s24, 0x60000
	s_addc_u32 s19, s25, 0
	s_add_i32 s53, s54, s38
	v_lshl_add_u64 v[162:163], s[18:19], 0, v[128:129]
	s_mov_b32 m0, s53
	s_nop 0
	global_load_lds_dwordx4 v[162:163], off
	v_lshl_add_u64 v[162:163], s[18:19], 0, v[132:133]
	s_add_i32 m0, s53, 0x2000
	s_nop 0
	global_load_lds_dwordx4 v[162:163], off
	s_waitcnt vmcnt(6)
	s_barrier
	s_setprio 1
	v_mfma_f32_16x16x32_bf16 v[52:55], v[214:217], v[180:183], v[52:55]
	v_mfma_f32_16x16x32_bf16 v[48:51], v[222:225], v[180:183], v[48:51]
	v_mfma_f32_16x16x32_bf16 v[36:39], v[214:217], v[188:191], v[36:39]
	v_mfma_f32_16x16x32_bf16 v[32:35], v[222:225], v[188:191], v[32:35]
	v_mfma_f32_16x16x32_bf16 v[20:23], v[214:217], v[198:201], v[20:23]
	v_mfma_f32_16x16x32_bf16 v[16:19], v[222:225], v[198:201], v[16:19]
	v_mfma_f32_16x16x32_bf16 v[4:7], v[214:217], v[206:209], v[4:7]
	v_mfma_f32_16x16x32_bf16 v[0:3], v[222:225], v[206:209], v[0:3]
	v_mfma_f32_16x16x32_bf16 v[52:55], v[218:221], v[184:187], v[52:55]
	v_mfma_f32_16x16x32_bf16 v[48:51], v[226:229], v[184:187], v[48:51]
	v_mfma_f32_16x16x32_bf16 v[36:39], v[218:221], v[194:197], v[36:39]
	v_mfma_f32_16x16x32_bf16 v[32:35], v[226:229], v[194:197], v[32:35]
	v_mfma_f32_16x16x32_bf16 v[20:23], v[218:221], v[202:205], v[20:23]
	v_mfma_f32_16x16x32_bf16 v[16:19], v[226:229], v[202:205], v[16:19]
	v_mfma_f32_16x16x32_bf16 v[4:7], v[218:221], v[210:213], v[4:7]
	v_mfma_f32_16x16x32_bf16 v[0:3], v[226:229], v[210:213], v[0:3]
	s_setprio 0
	s_add_i32 s53, 0, 0x18000
	v_add_u32_e32 v161, s53, v144
	s_barrier
	ds_read_b128 v[162:165], v161
	ds_read_b128 v[166:169], v161 offset:1024
	ds_read_b128 v[170:173], v161 offset:2048
	ds_read_b128 v[176:179], v161 offset:3072
	s_add_u32 s18, s28, 0x60000
	s_addc_u32 s19, s29, 0
	s_mov_b32 m0, s41
	v_lshl_add_u64 v[214:215], s[18:19], 0, v[128:129]
	ds_read_b128 v[180:183], v160 offset:32768
	ds_read_b128 v[184:187], v160 offset:33792
	ds_read_b128 v[188:191], v160 offset:34816
	ds_read_b128 v[194:197], v160 offset:35840
	ds_read_b128 v[198:201], v160 offset:36864
	ds_read_b128 v[202:205], v160 offset:37888
	ds_read_b128 v[206:209], v160 offset:38912
	ds_read_b128 v[210:213], v160 offset:39936
	global_load_lds_dwordx4 v[214:215], off
	v_lshl_add_u64 v[214:215], s[18:19], 0, v[132:133]
	s_mov_b32 m0, s42
	s_nop 0
	global_load_lds_dwordx4 v[214:215], off
	s_waitcnt lgkmcnt(8)
	s_barrier
	s_waitcnt lgkmcnt(0)
	s_setprio 1
	s_waitcnt lgkmcnt(0)
	v_mfma_f32_16x16x32_bf16 v[124:127], v[162:165], v[180:183], v[124:127]
	v_mfma_f32_16x16x32_bf16 v[120:123], v[170:173], v[180:183], v[120:123]
	v_mfma_f32_16x16x32_bf16 v[108:111], v[162:165], v[188:191], v[108:111]
	v_mfma_f32_16x16x32_bf16 v[104:107], v[170:173], v[188:191], v[104:107]
	v_mfma_f32_16x16x32_bf16 v[92:95], v[162:165], v[198:201], v[92:95]
	v_mfma_f32_16x16x32_bf16 v[88:91], v[170:173], v[198:201], v[88:91]
	v_mfma_f32_16x16x32_bf16 v[76:79], v[162:165], v[206:209], v[76:79]
	v_mfma_f32_16x16x32_bf16 v[72:75], v[170:173], v[206:209], v[72:75]
	v_mfma_f32_16x16x32_bf16 v[124:127], v[166:169], v[184:187], v[124:127]
	v_mfma_f32_16x16x32_bf16 v[120:123], v[176:179], v[184:187], v[120:123]
	v_mfma_f32_16x16x32_bf16 v[108:111], v[166:169], v[194:197], v[108:111]
	v_mfma_f32_16x16x32_bf16 v[104:107], v[176:179], v[194:197], v[104:107]
	v_mfma_f32_16x16x32_bf16 v[92:95], v[166:169], v[202:205], v[92:95]
	v_mfma_f32_16x16x32_bf16 v[88:91], v[176:179], v[202:205], v[88:91]
	v_mfma_f32_16x16x32_bf16 v[76:79], v[166:169], v[210:213], v[76:79]
	v_mfma_f32_16x16x32_bf16 v[72:75], v[176:179], v[210:213], v[72:75]
	s_setprio 0
	s_barrier
	s_add_i32 s28, 0, 0x1c000
	s_add_i32 s18, s53, s38
	v_add_u32_e32 v161, s28, v144
	v_lshl_add_u64 v[140:141], v[140:141], 0, s[2:3]
	s_mov_b32 m0, s18
	ds_read_b128 v[214:217], v161
	ds_read_b128 v[218:221], v161 offset:1024
	ds_read_b128 v[222:225], v161 offset:2048
	ds_read_b128 v[226:229], v161 offset:3072
	global_load_lds_dwordx4 v[140:141], off
	v_lshl_add_u64 v[140:141], v[230:231], 0, s[2:3]
	s_add_i32 m0, s18, 0x2000
	s_nop 0
	global_load_lds_dwordx4 v[140:141], off
	s_barrier
	s_waitcnt lgkmcnt(0)
	s_setprio 1
	s_waitcnt lgkmcnt(0)
	v_mfma_f32_16x16x32_bf16 v[116:119], v[214:217], v[180:183], v[116:119]
	v_mfma_f32_16x16x32_bf16 v[112:115], v[222:225], v[180:183], v[112:115]
	v_mfma_f32_16x16x32_bf16 v[100:103], v[214:217], v[188:191], v[100:103]
	v_mfma_f32_16x16x32_bf16 v[96:99], v[222:225], v[188:191], v[96:99]
	v_mfma_f32_16x16x32_bf16 v[84:87], v[214:217], v[198:201], v[84:87]
	v_mfma_f32_16x16x32_bf16 v[80:83], v[222:225], v[198:201], v[80:83]
	v_mfma_f32_16x16x32_bf16 v[68:71], v[214:217], v[206:209], v[68:71]
	v_mfma_f32_16x16x32_bf16 v[64:67], v[222:225], v[206:209], v[64:67]
	v_mfma_f32_16x16x32_bf16 v[116:119], v[218:221], v[184:187], v[116:119]
	v_mfma_f32_16x16x32_bf16 v[112:115], v[226:229], v[184:187], v[112:115]
	v_mfma_f32_16x16x32_bf16 v[100:103], v[218:221], v[194:197], v[100:103]
	v_mfma_f32_16x16x32_bf16 v[96:99], v[226:229], v[194:197], v[96:99]
	v_mfma_f32_16x16x32_bf16 v[84:87], v[218:221], v[202:205], v[84:87]
	v_mfma_f32_16x16x32_bf16 v[80:83], v[226:229], v[202:205], v[80:83]
	v_mfma_f32_16x16x32_bf16 v[68:71], v[218:221], v[210:213], v[68:71]
	v_mfma_f32_16x16x32_bf16 v[64:67], v[226:229], v[210:213], v[64:67]
	s_setprio 0
	s_mov_b32 m0, s43
	v_lshl_add_u64 v[140:141], v[232:233], 0, s[2:3]
	s_barrier
	ds_read_b128 v[180:183], v160 offset:49152
	ds_read_b128 v[184:187], v160 offset:50176
	ds_read_b128 v[188:191], v160 offset:51200
	ds_read_b128 v[194:197], v160 offset:52224
	ds_read_b128 v[198:201], v160 offset:53248
	ds_read_b128 v[202:205], v160 offset:54272
	ds_read_b128 v[206:209], v160 offset:55296
	ds_read_b128 v[210:213], v160 offset:56320
	global_load_lds_dwordx4 v[140:141], off
	v_lshl_add_u64 v[140:141], v[234:235], 0, s[2:3]
	s_mov_b32 m0, s44
	s_nop 0
	global_load_lds_dwordx4 v[140:141], off
	s_barrier
; #define G_STAGE(bufoff, gbase, voff) do { _Pragma("unroll") for (int _i = 0; _i < 2; ++_i) \
;         __builtin_amdgcn_global_load_lds((const unsigned*)((const char*)(gbase) + (voff)[_i]), (LAS unsigned*)(lds + (bufoff) + ldsw + _i * 8192), 16, 0, 0); } while (0)
; #define G_LDA(dst, b, h) do { _Pragma("unroll") for (int m = 0; m < 4; ++m) _Pragma("unroll") for (int k = 0; k < 2; ++k) dst[m][k] = *(const LAS bf16x8*)(lds + G_SA(b, h) + aoff + m * 2048 + k * 1024); } while (0)
; #define G_LDB(dst, b, h) do { _Pragma("unroll") for (int n = 0; n < 2; ++n) _Pragma("unroll") for (int k = 0; k < 2; ++k) dst[n][k] = *(const LAS bf16x8*)(lds + G_SB(b, h) + boff + n * 2048 + k * 1024); } while (0)
; #define G_WAIT_V(n) asm volatile("s_waitcnt vmcnt(" #n ")" ::: "memory")
; #define G_WAIT_L(n) asm volatile("s_waitcnt lgkmcnt(" #n ")" ::: "memory")
; #define G_BAR __builtin_amdgcn_s_barrier()
; #define G_SCHED __builtin_amdgcn_sched_barrier(0)
; template <bool PERM, class Dec, class Epi>
; DI void gemm_phase(LAS unsigned char* lds, const int nM, const int nN, const int K, const int lda, const int ldb, const Dec& dec, const Epi& epi, const int vb, const int panel = -1) {
;     ...
;             G_LDB(B0, 1, 0); G_SCHED; G_LDA(At, 1, 0); G_STAGE(G_SA(0, 1), a2 + hstepA, voffA);
;             G_WAIT_L(8); G_BAR; G_WAIT_L(0); G_MMA(0, 0, At, B0); G_BAR; G_SCHED;
;             G_LDB(B1, 1, 1); G_STAGE(G_SB(1, 0), b3, voffB);
;             G_BAR; G_WAIT_L(0); G_MMA(0, 1, At, B1); G_BAR;
;             G_LDA(At, 1, 1); G_STAGE(G_SA(1, 0), a3, voffA);
;             G_BAR; G_WAIT_L(0); G_MMA(1, 0, At, B0); G_BAR; G_SCHED;
;             G_STAGE(G_SB(1, 1), b3 + hstepB, voffB);
;             G_WAIT_V(6); G_BAR; G_MMA(1, 1, At, B1); G_BAR;
;         }
; __global__ void __launch_bounds__(512) hybrid_fwd(Params p) {
;     ...
;                       for (int m = 0; m < 4; ++m) { const int rl = ai * 128 + wr * 64 + m * 16 + fr; const size_t ro = (size_t)(pm * 256 + rl) * 1024 + pn * 256 + wc * 32 + 4 * fq;
;                           float ssq = 0.f;
; #pragma unroll
;                           for (int bj = 0; bj < 2; ++bj)
; #pragma unroll
;                               for (int n = 0; n < 2; ++n) { const size_t o = ro + bj * 128 + n * 16; const u32x2 xb = *(const u32x2*)(U + o);
	s_waitcnt lgkmcnt(0)
	s_setprio 1
	s_waitcnt lgkmcnt(0)
	v_mfma_f32_16x16x32_bf16 v[60:63], v[162:165], v[180:183], v[60:63]
	v_mfma_f32_16x16x32_bf16 v[56:59], v[170:173], v[180:183], v[56:59]
	v_mfma_f32_16x16x32_bf16 v[44:47], v[162:165], v[188:191], v[44:47]
	v_mfma_f32_16x16x32_bf16 v[40:43], v[170:173], v[188:191], v[40:43]
	v_mfma_f32_16x16x32_bf16 v[28:31], v[162:165], v[198:201], v[28:31]
	v_mfma_f32_16x16x32_bf16 v[24:27], v[170:173], v[198:201], v[24:27]
	v_mfma_f32_16x16x32_bf16 v[12:15], v[162:165], v[206:209], v[12:15]
	v_mfma_f32_16x16x32_bf16 v[8:11], v[170:173], v[206:209], v[8:11]
	v_mfma_f32_16x16x32_bf16 v[60:63], v[166:169], v[184:187], v[60:63]
	v_mfma_f32_16x16x32_bf16 v[56:59], v[176:179], v[184:187], v[56:59]
	v_mfma_f32_16x16x32_bf16 v[44:47], v[166:169], v[194:197], v[44:47]
	v_mfma_f32_16x16x32_bf16 v[40:43], v[176:179], v[194:197], v[40:43]
	v_mfma_f32_16x16x32_bf16 v[28:31], v[166:169], v[202:205], v[28:31]
	v_mfma_f32_16x16x32_bf16 v[24:27], v[176:179], v[202:205], v[24:27]
	v_mfma_f32_16x16x32_bf16 v[12:15], v[166:169], v[210:213], v[12:15]
	v_mfma_f32_16x16x32_bf16 v[8:11], v[176:179], v[210:213], v[8:11]
	s_setprio 0
	s_barrier
	s_add_u32 s18, s24, 0x60080
	s_addc_u32 s19, s25, 0
	s_add_i32 s24, s28, s38
	v_lshl_add_u64 v[140:141], s[18:19], 0, v[128:129]
	s_mov_b32 m0, s24
	s_nop 0
	global_load_lds_dwordx4 v[140:141], off
	v_lshl_add_u64 v[140:141], s[18:19], 0, v[132:133]
	s_add_i32 m0, s24, 0x2000
	s_nop 0
	global_load_lds_dwordx4 v[140:141], off
	s_waitcnt vmcnt(6)
	s_barrier
	s_setprio 1
	v_mfma_f32_16x16x32_bf16 v[52:55], v[214:217], v[180:183], v[52:55]
	v_mfma_f32_16x16x32_bf16 v[48:51], v[222:225], v[180:183], v[48:51]
	v_mfma_f32_16x16x32_bf16 v[36:39], v[214:217], v[188:191], v[36:39]
	v_mfma_f32_16x16x32_bf16 v[32:35], v[222:225], v[188:191], v[32:35]
	v_mfma_f32_16x16x32_bf16 v[20:23], v[214:217], v[198:201], v[20:23]
	v_mfma_f32_16x16x32_bf16 v[16:19], v[222:225], v[198:201], v[16:19]
	v_mfma_f32_16x16x32_bf16 v[4:7], v[214:217], v[206:209], v[4:7]
	v_mfma_f32_16x16x32_bf16 v[0:3], v[222:225], v[206:209], v[0:3]
	v_mfma_f32_16x16x32_bf16 v[52:55], v[218:221], v[184:187], v[52:55]
	v_mfma_f32_16x16x32_bf16 v[48:51], v[226:229], v[184:187], v[48:51]
	v_mfma_f32_16x16x32_bf16 v[36:39], v[218:221], v[194:197], v[36:39]
	v_mfma_f32_16x16x32_bf16 v[32:35], v[226:229], v[194:197], v[32:35]
	v_mfma_f32_16x16x32_bf16 v[20:23], v[218:221], v[202:205], v[20:23]
	v_mfma_f32_16x16x32_bf16 v[16:19], v[226:229], v[202:205], v[16:19]
	v_mfma_f32_16x16x32_bf16 v[4:7], v[218:221], v[210:213], v[4:7]
	v_mfma_f32_16x16x32_bf16 v[0:3], v[226:229], v[210:213], v[0:3]
	s_setprio 0
	s_add_i32 s52, s52, 2
	s_add_u32 s50, s50, 0x100
	s_addc_u32 s51, s51, 0
	s_cmp_gt_u32 s52, 21
	s_mov_b64 s[18:19], s[22:23]
	s_barrier
	s_cbranch_scc0 .LBB0_924
	s_lshl_b32 s22, s49, 8
	s_lshl_b32 s18, s48, 8
	v_add_u32_e32 v162, s22, v143
	s_ashr_i32 s19, s18, 31
	v_ashrrev_i32_e32 v163, 31, v162
	v_mov_b32_e32 v141, s19
	v_or_b32_e32 v140, s18, v134
	v_lshlrev_b64 v[162:163], 10, v[162:163]
	v_lshl_add_u64 v[162:163], v[140:141], 0, v[162:163]
	v_lshlrev_b64 v[164:165], 1, v[162:163]
	v_lshl_add_u64 v[162:163], s[20:21], 0, v[164:165]
	v_or_b32_e32 v168, 32, v164
	v_mov_b32_e32 v169, v165
	v_add_u32_e32 v230, s22, v143
	v_ashrrev_i32_e32 v231, 31, v230
	v_lshlrev_b64 v[230:231], 10, v[230:231]
	v_lshl_add_u64 v[230:231], v[140:141], 0, v[230:231]
	v_lshlrev_b64 v[230:231], 1, v[230:231]
	v_lshl_add_u64 v[230:231], s[20:21], 0, v[230:231]
	global_load_dwordx2 v[194:195], v[230:231], off
	global_load_dwordx2 v[196:197], v[230:231], off offset:32
	global_load_dwordx2 v[198:199], v[230:231], off offset:256
	global_load_dwordx2 v[200:201], v[230:231], off offset:288
	v_add_u32_e32 v230, s22, v146
	v_ashrrev_i32_e32 v231, 31, v230
	v_lshlrev_b64 v[230:231], 10, v[230:231]
	v_lshl_add_u64 v[230:231], v[140:141], 0, v[230:231]
	v_lshlrev_b64 v[230:231], 1, v[230:231]
	v_lshl_add_u64 v[230:231], s[20:21], 0, v[230:231]
	global_load_dwordx2 v[202:203], v[230:231], off
	global_load_dwordx2 v[204:205], v[230:231], off offset:32
	global_load_dwordx2 v[206:207], v[230:231], off offset:256
	global_load_dwordx2 v[208:209], v[230:231], off offset:288
	v_add_u32_e32 v230, s22, v148
	v_ashrrev_i32_e32 v231, 31, v230
	v_lshlrev_b64 v[230:231], 10, v[230:231]
	v_lshl_add_u64 v[230:231], v[140:141], 0, v[230:231]
	v_lshlrev_b64 v[230:231], 1, v[230:231]
	v_lshl_add_u64 v[230:231], s[20:21], 0, v[230:231]
	global_load_dwordx2 v[210:211], v[230:231], off
	global_load_dwordx2 v[212:213], v[230:231], off offset:32
	global_load_dwordx2 v[214:215], v[230:231], off offset:256
	global_load_dwordx2 v[216:217], v[230:231], off offset:288
	v_add_u32_e32 v230, s22, v150
	v_ashrrev_i32_e32 v231, 31, v230
	v_lshlrev_b64 v[230:231], 10, v[230:231]
	v_lshl_add_u64 v[230:231], v[140:141], 0, v[230:231]
	v_lshlrev_b64 v[230:231], 1, v[230:231]
	v_lshl_add_u64 v[230:231], s[20:21], 0, v[230:231]
	global_load_dwordx2 v[218:219], v[230:231], off
	global_load_dwordx2 v[220:221], v[230:231], off offset:32
	global_load_dwordx2 v[222:223], v[230:231], off offset:256
	global_load_dwordx2 v[224:225], v[230:231], off offset:288
	s_waitcnt vmcnt(12)
; DI float bflo(unsigned u) { return __uint_as_float(u << 16); }
; DI float bfhi(unsigned u) { return __uint_as_float(u & 0xffff0000u); }
; __global__ void __launch_bounds__(512) hybrid_fwd(Params p) {
;     ...
;                               for (int n = 0; n < 2; ++n) { const size_t o = ro + bj * 128 + n * 16; const u32x2 xb = *(const u32x2*)(U + o);
;                                   const f32x4 v = (f32x4){bflo(xb[0]), bfhi(xb[0]), bflo(xb[1]), bfhi(xb[1])} + acc[ai][bj][m][n];
	v_lshlrev_b32_e32 v226, 16, v194
	v_and_b32_e32 v227, 0xffff0000, v194
	v_lshlrev_b32_e32 v228, 16, v195
	v_and_b32_e32 v229, 0xffff0000, v195
	v_pk_add_f32 v[124:125], v[124:125], v[226:227]
	v_pk_add_f32 v[126:127], v[126:127], v[228:229]
	v_lshlrev_b32_e32 v226, 16, v196
	v_and_b32_e32 v227, 0xffff0000, v196
	v_lshlrev_b32_e32 v228, 16, v197
	v_and_b32_e32 v229, 0xffff0000, v197
	v_pk_add_f32 v[120:121], v[120:121], v[226:227]
	v_pk_add_f32 v[122:123], v[122:123], v[228:229]
	v_lshlrev_b32_e32 v226, 16, v198
	v_and_b32_e32 v227, 0xffff0000, v198
	v_lshlrev_b32_e32 v228, 16, v199
	v_and_b32_e32 v229, 0xffff0000, v199
	v_pk_add_f32 v[116:117], v[116:117], v[226:227]
	v_pk_add_f32 v[118:119], v[118:119], v[228:229]
	v_lshlrev_b32_e32 v226, 16, v200
	v_and_b32_e32 v227, 0xffff0000, v200
	v_lshlrev_b32_e32 v228, 16, v201
	v_and_b32_e32 v229, 0xffff0000, v201
	v_pk_add_f32 v[112:113], v[112:113], v[226:227]
	v_pk_add_f32 v[114:115], v[114:115], v[228:229]
	v_add_u32_e32 v230, s22, v152
	v_ashrrev_i32_e32 v231, 31, v230
	v_lshlrev_b64 v[230:231], 10, v[230:231]
	v_lshl_add_u64 v[230:231], v[140:141], 0, v[230:231]
	v_lshlrev_b64 v[230:231], 1, v[230:231]
	v_lshl_add_u64 v[230:231], s[20:21], 0, v[230:231]
	global_load_dwordx2 v[194:195], v[230:231], off
	global_load_dwordx2 v[196:197], v[230:231], off offset:32
	global_load_dwordx2 v[198:199], v[230:231], off offset:256
	global_load_dwordx2 v[200:201], v[230:231], off offset:288
	s_waitcnt vmcnt(12)
	v_lshlrev_b32_e32 v226, 16, v202
	v_and_b32_e32 v227, 0xffff0000, v202
	v_lshlrev_b32_e32 v228, 16, v203
	v_and_b32_e32 v229, 0xffff0000, v203
	v_pk_add_f32 v[108:109], v[108:109], v[226:227]
	v_pk_add_f32 v[110:111], v[110:111], v[228:229]
	v_lshlrev_b32_e32 v226, 16, v204
	v_and_b32_e32 v227, 0xffff0000, v204
	v_lshlrev_b32_e32 v228, 16, v205
	v_and_b32_e32 v229, 0xffff0000, v205
	v_pk_add_f32 v[104:105], v[104:105], v[226:227]
	v_pk_add_f32 v[106:107], v[106:107], v[228:229]
	v_lshlrev_b32_e32 v226, 16, v206
	v_and_b32_e32 v227, 0xffff0000, v206
	v_lshlrev_b32_e32 v228, 16, v207
	v_and_b32_e32 v229, 0xffff0000, v207
	v_pk_add_f32 v[100:101], v[100:101], v[226:227]
	v_pk_add_f32 v[102:103], v[102:103], v[228:229]
	v_lshlrev_b32_e32 v226, 16, v208
	v_and_b32_e32 v227, 0xffff0000, v208
	v_lshlrev_b32_e32 v228, 16, v209
	v_and_b32_e32 v229, 0xffff0000, v209
	v_pk_add_f32 v[96:97], v[96:97], v[226:227]
	v_pk_add_f32 v[98:99], v[98:99], v[228:229]
	v_add_u32_e32 v230, s22, v154
	v_ashrrev_i32_e32 v231, 31, v230
	v_lshlrev_b64 v[230:231], 10, v[230:231]
	v_lshl_add_u64 v[230:231], v[140:141], 0, v[230:231]
	v_lshlrev_b64 v[230:231], 1, v[230:231]
	v_lshl_add_u64 v[230:231], s[20:21], 0, v[230:231]
	global_load_dwordx2 v[202:203], v[230:231], off
	global_load_dwordx2 v[204:205], v[230:231], off offset:32
	global_load_dwordx2 v[206:207], v[230:231], off offset:256
	global_load_dwordx2 v[208:209], v[230:231], off offset:288
	s_waitcnt vmcnt(12)
	v_lshlrev_b32_e32 v226, 16, v210
	v_and_b32_e32 v227, 0xffff0000, v210
	v_lshlrev_b32_e32 v228, 16, v211
	v_and_b32_e32 v229, 0xffff0000, v211
	v_pk_add_f32 v[92:93], v[92:93], v[226:227]
	v_pk_add_f32 v[94:95], v[94:95], v[228:229]
	v_lshlrev_b32_e32 v226, 16, v212
	v_and_b32_e32 v227, 0xffff0000, v212
	v_lshlrev_b32_e32 v228, 16, v213
	v_and_b32_e32 v229, 0xffff0000, v213
	v_pk_add_f32 v[88:89], v[88:89], v[226:227]
	v_pk_add_f32 v[90:91], v[90:91], v[228:229]
	v_lshlrev_b32_e32 v226, 16, v214
	v_and_b32_e32 v227, 0xffff0000, v214
	v_lshlrev_b32_e32 v228, 16, v215
	v_and_b32_e32 v229, 0xffff0000, v215
	v_pk_add_f32 v[84:85], v[84:85], v[226:227]
	v_pk_add_f32 v[86:87], v[86:87], v[228:229]
	v_lshlrev_b32_e32 v226, 16, v216
	v_and_b32_e32 v227, 0xffff0000, v216
	v_lshlrev_b32_e32 v228, 16, v217
	v_and_b32_e32 v229, 0xffff0000, v217
	v_pk_add_f32 v[80:81], v[80:81], v[226:227]
	v_pk_add_f32 v[82:83], v[82:83], v[228:229]
	v_add_u32_e32 v230, s22, v156
	v_ashrrev_i32_e32 v231, 31, v230
	v_lshlrev_b64 v[230:231], 10, v[230:231]
	v_lshl_add_u64 v[230:231], v[140:141], 0, v[230:231]
	v_lshlrev_b64 v[230:231], 1, v[230:231]
	v_lshl_add_u64 v[230:231], s[20:21], 0, v[230:231]
	global_load_dwordx2 v[210:211], v[230:231], off
	global_load_dwordx2 v[212:213], v[230:231], off offset:32
	global_load_dwordx2 v[214:215], v[230:231], off offset:256
	global_load_dwordx2 v[216:217], v[230:231], off offset:288
	s_waitcnt vmcnt(12)
	v_lshlrev_b32_e32 v226, 16, v218
	v_and_b32_e32 v227, 0xffff0000, v218
	v_lshlrev_b32_e32 v228, 16, v219
	v_and_b32_e32 v229, 0xffff0000, v219
	v_pk_add_f32 v[76:77], v[76:77], v[226:227]
	v_pk_add_f32 v[78:79], v[78:79], v[228:229]
	v_lshlrev_b32_e32 v226, 16, v220
	v_and_b32_e32 v227, 0xffff0000, v220
	v_lshlrev_b32_e32 v228, 16, v221
	v_and_b32_e32 v229, 0xffff0000, v221
	v_pk_add_f32 v[72:73], v[72:73], v[226:227]
	v_pk_add_f32 v[74:75], v[74:75], v[228:229]
	v_lshlrev_b32_e32 v226, 16, v222
	v_and_b32_e32 v227, 0xffff0000, v222
	v_lshlrev_b32_e32 v228, 16, v223
	v_and_b32_e32 v229, 0xffff0000, v223
	v_pk_add_f32 v[68:69], v[68:69], v[226:227]
	v_pk_add_f32 v[70:71], v[70:71], v[228:229]
	v_lshlrev_b32_e32 v226, 16, v224
	v_and_b32_e32 v227, 0xffff0000, v224
	v_lshlrev_b32_e32 v228, 16, v225
	v_and_b32_e32 v229, 0xffff0000, v225
	v_pk_add_f32 v[64:65], v[64:65], v[226:227]
	v_pk_add_f32 v[66:67], v[66:67], v[228:229]
	v_add_u32_e32 v230, s22, v158
	v_ashrrev_i32_e32 v231, 31, v230
	v_lshlrev_b64 v[230:231], 10, v[230:231]
	v_lshl_add_u64 v[230:231], v[140:141], 0, v[230:231]
	v_lshlrev_b64 v[230:231], 1, v[230:231]
	v_lshl_add_u64 v[230:231], s[20:21], 0, v[230:231]
	global_load_dwordx2 v[218:219], v[230:231], off
	global_load_dwordx2 v[220:221], v[230:231], off offset:32
	global_load_dwordx2 v[222:223], v[230:231], off offset:256
	global_load_dwordx2 v[224:225], v[230:231], off offset:288
	s_waitcnt vmcnt(12)
; DI unsigned pk2(float a, float b) { f32x2 v = {a, b}; bf2_t r = __builtin_convertvector(v, bf2_t); return __builtin_bit_cast(unsigned, r); }
; DI float bflo(unsigned u) { return __uint_as_float(u << 16); }
; DI float bfhi(unsigned u) { return __uint_as_float(u & 0xffff0000u); }
; __global__ void __launch_bounds__(512) hybrid_fwd(Params p) {
;     ...
;                               for (int n = 0; n < 2; ++n) { const size_t o = ro + bj * 128 + n * 16; const u32x2 xb = *(const u32x2*)(U + o);
;                                   const f32x4 v = (f32x4){bflo(xb[0]), bfhi(xb[0]), bflo(xb[1]), bfhi(xb[1])} + acc[ai][bj][m][n];
;                                   u32x2 wv; wv[0] = pk2(v[0], v[1]); wv[1] = pk2(v[2], v[3]); *(u32x2*)(X2B + o) = wv;
;                                   ssq += v[0] * v[0] + v[1] * v[1] + v[2] * v[2] + v[3] * v[3]; }
;                           ssq += __shfl_xor(ssq, 16); ssq += __shfl_xor(ssq, 32);
;                           if (fq == 0) __hip_atomic_fetch_add((float*)(shm + 131072) + rl, ssq, __ATOMIC_RELAXED, __HIP_MEMORY_SCOPE_WORKGROUP); } }, vb, panel);
	v_lshlrev_b32_e32 v226, 16, v194
	v_and_b32_e32 v227, 0xffff0000, v194
	v_lshlrev_b32_e32 v228, 16, v195
	v_and_b32_e32 v229, 0xffff0000, v195
	v_pk_add_f32 v[60:61], v[60:61], v[226:227]
	v_pk_add_f32 v[62:63], v[62:63], v[228:229]
	v_lshlrev_b32_e32 v226, 16, v196
	v_and_b32_e32 v227, 0xffff0000, v196
	v_lshlrev_b32_e32 v228, 16, v197
	v_and_b32_e32 v229, 0xffff0000, v197
	v_pk_add_f32 v[56:57], v[56:57], v[226:227]
	v_pk_add_f32 v[58:59], v[58:59], v[228:229]
	v_lshlrev_b32_e32 v226, 16, v198
	v_and_b32_e32 v227, 0xffff0000, v198
	v_lshlrev_b32_e32 v228, 16, v199
	v_and_b32_e32 v229, 0xffff0000, v199
	v_pk_add_f32 v[52:53], v[52:53], v[226:227]
	v_pk_add_f32 v[54:55], v[54:55], v[228:229]
	v_lshlrev_b32_e32 v226, 16, v200
	v_and_b32_e32 v227, 0xffff0000, v200
	v_lshlrev_b32_e32 v228, 16, v201
	v_and_b32_e32 v229, 0xffff0000, v201
	v_pk_add_f32 v[48:49], v[48:49], v[226:227]
	v_pk_add_f32 v[50:51], v[50:51], v[228:229]
	s_waitcnt vmcnt(8)
	v_lshlrev_b32_e32 v226, 16, v202
	v_and_b32_e32 v227, 0xffff0000, v202
	v_lshlrev_b32_e32 v228, 16, v203
	v_and_b32_e32 v229, 0xffff0000, v203
	v_pk_add_f32 v[44:45], v[44:45], v[226:227]
	v_pk_add_f32 v[46:47], v[46:47], v[228:229]
	v_lshlrev_b32_e32 v226, 16, v204
	v_and_b32_e32 v227, 0xffff0000, v204
	v_lshlrev_b32_e32 v228, 16, v205
	v_and_b32_e32 v229, 0xffff0000, v205
	v_pk_add_f32 v[40:41], v[40:41], v[226:227]
	v_pk_add_f32 v[42:43], v[42:43], v[228:229]
	v_lshlrev_b32_e32 v226, 16, v206
	v_and_b32_e32 v227, 0xffff0000, v206
	v_lshlrev_b32_e32 v228, 16, v207
	v_and_b32_e32 v229, 0xffff0000, v207
	v_pk_add_f32 v[36:37], v[36:37], v[226:227]
	v_pk_add_f32 v[38:39], v[38:39], v[228:229]
	v_lshlrev_b32_e32 v226, 16, v208
	v_and_b32_e32 v227, 0xffff0000, v208
	v_lshlrev_b32_e32 v228, 16, v209
	v_and_b32_e32 v229, 0xffff0000, v209
	v_pk_add_f32 v[32:33], v[32:33], v[226:227]
	v_pk_add_f32 v[34:35], v[34:35], v[228:229]
	s_waitcnt vmcnt(4)
	v_lshlrev_b32_e32 v226, 16, v210
	v_and_b32_e32 v227, 0xffff0000, v210
	v_lshlrev_b32_e32 v228, 16, v211
	v_and_b32_e32 v229, 0xffff0000, v211
	v_pk_add_f32 v[28:29], v[28:29], v[226:227]
	v_pk_add_f32 v[30:31], v[30:31], v[228:229]
	v_lshlrev_b32_e32 v226, 16, v212
	v_and_b32_e32 v227, 0xffff0000, v212
	v_lshlrev_b32_e32 v228, 16, v213
	v_and_b32_e32 v229, 0xffff0000, v213
	v_pk_add_f32 v[24:25], v[24:25], v[226:227]
	v_pk_add_f32 v[26:27], v[26:27], v[228:229]
	v_lshlrev_b32_e32 v226, 16, v214
	v_and_b32_e32 v227, 0xffff0000, v214
	v_lshlrev_b32_e32 v228, 16, v215
	v_and_b32_e32 v229, 0xffff0000, v215
	v_pk_add_f32 v[20:21], v[20:21], v[226:227]
	v_pk_add_f32 v[22:23], v[22:23], v[228:229]
	v_lshlrev_b32_e32 v226, 16, v216
	v_and_b32_e32 v227, 0xffff0000, v216
	v_lshlrev_b32_e32 v228, 16, v217
	v_and_b32_e32 v229, 0xffff0000, v217
	v_pk_add_f32 v[16:17], v[16:17], v[226:227]
	v_pk_add_f32 v[18:19], v[18:19], v[228:229]
	s_waitcnt vmcnt(0)
	v_lshlrev_b32_e32 v226, 16, v218
	v_and_b32_e32 v227, 0xffff0000, v218
	v_lshlrev_b32_e32 v228, 16, v219
	v_and_b32_e32 v229, 0xffff0000, v219
	v_pk_add_f32 v[12:13], v[12:13], v[226:227]
	v_pk_add_f32 v[14:15], v[14:15], v[228:229]
	v_lshlrev_b32_e32 v226, 16, v220
	v_and_b32_e32 v227, 0xffff0000, v220
	v_lshlrev_b32_e32 v228, 16, v221
	v_and_b32_e32 v229, 0xffff0000, v221
	v_pk_add_f32 v[8:9], v[8:9], v[226:227]
	v_pk_add_f32 v[10:11], v[10:11], v[228:229]
	v_lshlrev_b32_e32 v226, 16, v222
	v_and_b32_e32 v227, 0xffff0000, v222
	v_lshlrev_b32_e32 v228, 16, v223
	v_and_b32_e32 v229, 0xffff0000, v223
	v_pk_add_f32 v[4:5], v[4:5], v[226:227]
	v_pk_add_f32 v[6:7], v[6:7], v[228:229]
	v_lshlrev_b32_e32 v226, 16, v224
	v_and_b32_e32 v227, 0xffff0000, v224
	v_lshlrev_b32_e32 v228, 16, v225
	v_and_b32_e32 v229, 0xffff0000, v225
	v_pk_add_f32 v[0:1], v[0:1], v[226:227]
	v_pk_add_f32 v[2:3], v[2:3], v[228:229]
	v_mbcnt_lo_u32_b32 v218, -1, 0
	v_mbcnt_hi_u32_b32 v218, -1, v218
	v_bfe_u32 v218, v218, 4, 1
	v_mul_u32_u24_e32 v218, 24, v218
	v_mov_b32_e32 v219, 0
	v_lshl_add_u64 v[162:163], s[20:21], 0, v[168:169]
	v_or_b32_e32 v172, 0x100, v164
	v_mov_b32_e32 v173, v165
	v_lshl_add_u64 v[162:163], s[20:21], 0, v[172:173]
	v_lshl_add_u64 v[178:179], s[58:59], 0, v[164:165]
	v_or_b32_e32 v164, 0x120, v164
	v_lshl_add_u64 v[162:163], s[20:21], 0, v[164:165]
	v_and_b32_e32 v162, 64, v174
	v_xor_b32_e32 v161, 16, v174
	v_add_u32_e32 v162, 64, v162
	v_xor_b32_e32 v163, 32, v174
	v_cmp_lt_i32_e32 vcc, v161, v162
	v_lshl_add_u64 v[168:169], s[58:59], 0, v[168:169]
	v_lshlrev_b32_e32 v182, 16, v166
	v_and_b32_e32 v183, 0xffff0000, v166
	v_lshlrev_b32_e32 v166, 16, v167
	v_and_b32_e32 v167, 0xffff0000, v167
	v_lshlrev_b32_e32 v166, 16, v170
	v_and_b32_e32 v167, 0xffff0000, v170
	v_lshlrev_b32_e32 v182, 16, v176
	v_and_b32_e32 v183, 0xffff0000, v176
	v_lshlrev_b32_e32 v184, 16, v180
	v_and_b32_e32 v185, 0xffff0000, v180
	v_cndmask_b32_e32 v161, v174, v161, vcc
	v_cmp_lt_i32_e32 vcc, v163, v162
	v_lshlrev_b32_e32 v170, 16, v171
	v_and_b32_e32 v171, 0xffff0000, v171
	v_cvt_pk_bf16_f32 v186, v124, v125
	v_mul_f32_e32 v125, v125, v125
	v_mov_b32_e32 v166, v112
	v_mov_b32_e32 v167, v113
	v_cvt_pk_bf16_f32 v112, v120, v121
	v_mul_f32_e32 v121, v121, v121
	v_cndmask_b32_e32 v163, v174, v163, vcc
	v_lshlrev_b32_e32 v176, 16, v177
	v_and_b32_e32 v177, 0xffff0000, v177
	v_fmac_f32_e32 v125, v124, v124
	v_mul_f32_e32 v124, v117, v117
	v_fmac_f32_e32 v121, v120, v120
	v_lshlrev_b32_e32 v162, 2, v161
	v_lshlrev_b32_e32 v161, 2, v163
	v_lshlrev_b32_e32 v180, 16, v181
	v_and_b32_e32 v181, 0xffff0000, v181
	v_mul_f32_e32 v163, v167, v167
	v_fmac_f32_e32 v125, v126, v126
	v_fmac_f32_e32 v124, v116, v116
	v_fmac_f32_e32 v121, v122, v122
	v_cvt_pk_bf16_f32 v113, v122, v123
	v_fmac_f32_e32 v163, v166, v166
	v_fmac_f32_e32 v125, v127, v127
	v_fmac_f32_e32 v124, v118, v118
	v_fmac_f32_e32 v121, v123, v123
	v_mov_b32_e32 v198, v112
	v_mov_b32_e32 v199, v113
	v_fmac_f32_e32 v163, v114, v114
	v_fmac_f32_e32 v124, v119, v119
	v_add_f32_e32 v112, v125, v121
	v_add_f32_e32 v112, v112, v124
	v_fmac_f32_e32 v163, v115, v115
	v_add_f32_e32 v120, v112, v163
	ds_bpermute_b32 v121, v162, v120
	v_cvt_pk_bf16_f32 v112, v116, v117
	v_cvt_pk_bf16_f32 v113, v118, v119
	v_lshl_add_u64 v[116:117], s[58:59], 0, v[172:173]
	v_mov_b32_e32 v200, v112
	v_mov_b32_e32 v201, v113
	v_lshl_add_u64 v[204:205], v[116:117], 0, v[218:219]
	s_waitcnt lgkmcnt(0)
	v_add_f32_e32 v112, v120, v121
	ds_bpermute_b32 v113, v161, v112
	v_cvt_pk_bf16_f32 v187, v126, v127
	v_cvt_pk_bf16_f32 v116, v166, v167
	v_cvt_pk_bf16_f32 v117, v114, v115
	v_lshl_add_u64 v[114:115], s[58:59], 0, v[164:165]
	v_mov_b32_e32 v196, v186
	v_mov_b32_e32 v197, v187
	v_lshl_add_u64 v[194:195], v[178:179], 0, v[218:219]
	s_nop 1
	v_permlane16_swap_b32_e32 v196, v198
	v_permlane16_swap_b32_e32 v197, v199
	global_store_dwordx4 v[194:195], v[196:199], off
	v_mov_b32_e32 v202, v116
	v_mov_b32_e32 v203, v117
	s_nop 1
	v_permlane16_swap_b32_e32 v200, v202
	v_permlane16_swap_b32_e32 v201, v203
	global_store_dwordx4 v[204:205], v[200:203], off
	s_and_saveexec_b64 s[18:19], s[0:1]
	s_cbranch_execz .LBB0_927
; DI unsigned pk2(float a, float b) { f32x2 v = {a, b}; bf2_t r = __builtin_convertvector(v, bf2_t); return __builtin_bit_cast(unsigned, r); }
; DI float bflo(unsigned u) { return __uint_as_float(u << 16); }
; DI float bfhi(unsigned u) { return __uint_as_float(u & 0xffff0000u); }
; __global__ void __launch_bounds__(512) hybrid_fwd(Params p) {
;     ...
;                       for (int m = 0; m < 4; ++m) { const int rl = ai * 128 + wr * 64 + m * 16 + fr; const size_t ro = (size_t)(pm * 256 + rl) * 1024 + pn * 256 + wc * 32 + 4 * fq;
;                           float ssq = 0.f;
; #pragma unroll
;                           for (int bj = 0; bj < 2; ++bj)
; #pragma unroll
;                               for (int n = 0; n < 2; ++n) { const size_t o = ro + bj * 128 + n * 16; const u32x2 xb = *(const u32x2*)(U + o);
;                                   const f32x4 v = (f32x4){bflo(xb[0]), bfhi(xb[0]), bflo(xb[1]), bfhi(xb[1])} + acc[ai][bj][m][n];
;                                   u32x2 wv; wv[0] = pk2(v[0], v[1]); wv[1] = pk2(v[2], v[3]); *(u32x2*)(X2B + o) = wv;
;                                   ssq += v[0] * v[0] + v[1] * v[1] + v[2] * v[2] + v[3] * v[3]; }
;                           ssq += __shfl_xor(ssq, 16); ssq += __shfl_xor(ssq, 32);
;                           if (fq == 0) __hip_atomic_fetch_add((float*)(shm + 131072) + rl, ssq, __ATOMIC_RELAXED, __HIP_MEMORY_SCOPE_WORKGROUP); } }, vb, panel);
	s_waitcnt lgkmcnt(0)
	v_add_f32_e32 v112, v112, v113
	ds_add_f32 v145, v112
.LBB0_927:
	s_or_b64 exec, exec, s[18:19]
	v_add_u32_e32 v112, s22, v146
	s_waitcnt lgkmcnt(0)
	v_ashrrev_i32_e32 v113, 31, v112
	v_lshlrev_b64 v[112:113], 10, v[112:113]
	v_lshl_add_u64 v[112:113], v[140:141], 0, v[112:113]
	v_lshlrev_b64 v[112:113], 1, v[112:113]
	v_lshl_add_u64 v[114:115], s[20:21], 0, v[112:113]
	v_or_b32_e32 v116, 32, v112
	v_mov_b32_e32 v117, v113
	v_lshl_add_u64 v[118:119], s[20:21], 0, v[116:117]
	v_or_b32_e32 v120, 0x100, v112
	v_mov_b32_e32 v121, v113
	v_lshl_add_u64 v[124:125], s[58:59], 0, v[112:113]
	v_or_b32_e32 v112, 0x120, v112
	v_lshl_add_u64 v[122:123], s[20:21], 0, v[120:121]
	v_lshl_add_u64 v[126:127], s[20:21], 0, v[112:113]
	v_lshl_add_u64 v[116:117], s[58:59], 0, v[116:117]
	v_lshlrev_b32_e32 v164, 16, v114
	v_and_b32_e32 v165, 0xffff0000, v114
	v_lshlrev_b32_e32 v114, 16, v115
	v_and_b32_e32 v115, 0xffff0000, v115
	v_lshlrev_b32_e32 v114, 16, v118
	v_and_b32_e32 v115, 0xffff0000, v118
	v_lshlrev_b32_e32 v164, 16, v122
	v_and_b32_e32 v165, 0xffff0000, v122
	v_lshlrev_b32_e32 v166, 16, v126
	v_and_b32_e32 v167, 0xffff0000, v126
	v_lshlrev_b32_e32 v118, 16, v119
	v_and_b32_e32 v119, 0xffff0000, v119
	v_cvt_pk_bf16_f32 v168, v108, v109
	v_mul_f32_e32 v109, v109, v109
	v_mov_b32_e32 v114, v96
	v_mov_b32_e32 v115, v97
	v_cvt_pk_bf16_f32 v96, v104, v105
	v_mul_f32_e32 v105, v105, v105
	v_lshlrev_b32_e32 v122, 16, v123
	v_and_b32_e32 v123, 0xffff0000, v123
	v_fmac_f32_e32 v109, v108, v108
	v_mul_f32_e32 v108, v101, v101
	v_fmac_f32_e32 v105, v104, v104
	v_lshlrev_b32_e32 v126, 16, v127
	v_and_b32_e32 v127, 0xffff0000, v127
	v_mul_f32_e32 v118, v115, v115
	v_fmac_f32_e32 v109, v110, v110
	v_fmac_f32_e32 v108, v100, v100
	v_fmac_f32_e32 v105, v106, v106
	v_cvt_pk_bf16_f32 v97, v106, v107
	v_fmac_f32_e32 v118, v114, v114
	v_fmac_f32_e32 v109, v111, v111
	v_fmac_f32_e32 v108, v102, v102
	v_fmac_f32_e32 v105, v107, v107
	v_mov_b32_e32 v210, v96
	v_mov_b32_e32 v211, v97
	v_fmac_f32_e32 v118, v98, v98
	v_fmac_f32_e32 v108, v103, v103
	v_add_f32_e32 v96, v109, v105
	v_add_f32_e32 v96, v96, v108
	v_fmac_f32_e32 v118, v99, v99
	v_add_f32_e32 v104, v96, v118
	ds_bpermute_b32 v105, v162, v104
	v_cvt_pk_bf16_f32 v96, v100, v101
	v_cvt_pk_bf16_f32 v97, v102, v103
	v_lshl_add_u64 v[100:101], s[58:59], 0, v[120:121]
	v_mov_b32_e32 v212, v96
	v_mov_b32_e32 v213, v97
	v_lshl_add_u64 v[216:217], v[100:101], 0, v[218:219]
	s_waitcnt lgkmcnt(0)
	v_add_f32_e32 v96, v104, v105
	ds_bpermute_b32 v97, v161, v96
	v_cvt_pk_bf16_f32 v169, v110, v111
	v_cvt_pk_bf16_f32 v100, v114, v115
	v_cvt_pk_bf16_f32 v101, v98, v99
	v_lshl_add_u64 v[98:99], s[58:59], 0, v[112:113]
	v_mov_b32_e32 v208, v168
	v_mov_b32_e32 v209, v169
	v_lshl_add_u64 v[206:207], v[124:125], 0, v[218:219]
	s_nop 1
	v_permlane16_swap_b32_e32 v208, v210
	v_permlane16_swap_b32_e32 v209, v211
	global_store_dwordx4 v[206:207], v[208:211], off
	v_mov_b32_e32 v214, v100
	v_mov_b32_e32 v215, v101
	s_nop 1
	v_permlane16_swap_b32_e32 v212, v214
	v_permlane16_swap_b32_e32 v213, v215
	global_store_dwordx4 v[216:217], v[212:215], off
	s_and_saveexec_b64 s[18:19], s[0:1]
	s_cbranch_execz .LBB0_929
	s_waitcnt lgkmcnt(0)
	v_add_f32_e32 v96, v96, v97
	ds_add_f32 v147, v96
.LBB0_929:
	s_or_b64 exec, exec, s[18:19]
	v_add_u32_e32 v96, s22, v148
	s_waitcnt lgkmcnt(0)
	v_ashrrev_i32_e32 v97, 31, v96
	v_lshlrev_b64 v[96:97], 10, v[96:97]
	v_lshl_add_u64 v[96:97], v[140:141], 0, v[96:97]
	v_lshlrev_b64 v[96:97], 1, v[96:97]
	v_lshl_add_u64 v[98:99], s[20:21], 0, v[96:97]
	v_or_b32_e32 v100, 32, v96
	v_mov_b32_e32 v101, v97
	v_lshl_add_u64 v[102:103], s[20:21], 0, v[100:101]
	v_or_b32_e32 v104, 0x100, v96
	v_mov_b32_e32 v105, v97
	v_lshl_add_u64 v[108:109], s[58:59], 0, v[96:97]
	v_or_b32_e32 v96, 0x120, v96
	v_lshl_add_u64 v[106:107], s[20:21], 0, v[104:105]
	v_lshl_add_u64 v[110:111], s[20:21], 0, v[96:97]
	v_lshl_add_u64 v[100:101], s[58:59], 0, v[100:101]
	v_lshlrev_b32_e32 v112, 16, v98
	v_and_b32_e32 v113, 0xffff0000, v98
	v_lshlrev_b32_e32 v98, 16, v99
	v_and_b32_e32 v99, 0xffff0000, v99
	v_lshlrev_b32_e32 v98, 16, v102
	v_and_b32_e32 v99, 0xffff0000, v102
	v_lshlrev_b32_e32 v112, 16, v106
	v_and_b32_e32 v113, 0xffff0000, v106
	v_lshlrev_b32_e32 v114, 16, v110
	v_and_b32_e32 v115, 0xffff0000, v110
	v_lshlrev_b32_e32 v102, 16, v103
	v_and_b32_e32 v103, 0xffff0000, v103
	v_cvt_pk_bf16_f32 v116, v92, v93
	v_mul_f32_e32 v93, v93, v93
	v_mov_b32_e32 v98, v80
	v_mov_b32_e32 v99, v81
	v_cvt_pk_bf16_f32 v80, v88, v89
	v_mul_f32_e32 v89, v89, v89
	v_lshlrev_b32_e32 v106, 16, v107
	v_and_b32_e32 v107, 0xffff0000, v107
	v_fmac_f32_e32 v93, v92, v92
	v_mul_f32_e32 v92, v85, v85
	v_fmac_f32_e32 v89, v88, v88
	v_lshlrev_b32_e32 v110, 16, v111
	v_and_b32_e32 v111, 0xffff0000, v111
	v_mul_f32_e32 v102, v99, v99
	v_fmac_f32_e32 v93, v94, v94
	v_fmac_f32_e32 v92, v84, v84
	v_fmac_f32_e32 v89, v90, v90
	v_cvt_pk_bf16_f32 v81, v90, v91
	v_fmac_f32_e32 v102, v98, v98
	v_fmac_f32_e32 v93, v95, v95
	v_fmac_f32_e32 v92, v86, v86
	v_fmac_f32_e32 v89, v91, v91
	v_mov_b32_e32 v198, v80
	v_mov_b32_e32 v199, v81
	v_fmac_f32_e32 v102, v82, v82
	v_fmac_f32_e32 v92, v87, v87
	v_add_f32_e32 v80, v93, v89
	v_add_f32_e32 v80, v80, v92
	v_fmac_f32_e32 v102, v83, v83
	v_add_f32_e32 v88, v80, v102
	ds_bpermute_b32 v89, v162, v88
	v_cvt_pk_bf16_f32 v80, v84, v85
	v_cvt_pk_bf16_f32 v81, v86, v87
	v_lshl_add_u64 v[84:85], s[58:59], 0, v[104:105]
	v_mov_b32_e32 v200, v80
	v_mov_b32_e32 v201, v81
	v_lshl_add_u64 v[204:205], v[84:85], 0, v[218:219]
	s_waitcnt lgkmcnt(0)
	v_add_f32_e32 v80, v88, v89
	ds_bpermute_b32 v81, v161, v80
	v_cvt_pk_bf16_f32 v117, v94, v95
	v_cvt_pk_bf16_f32 v84, v98, v99
	v_cvt_pk_bf16_f32 v85, v82, v83
	v_lshl_add_u64 v[82:83], s[58:59], 0, v[96:97]
	v_mov_b32_e32 v196, v116
	v_mov_b32_e32 v197, v117
	v_lshl_add_u64 v[194:195], v[108:109], 0, v[218:219]
	s_nop 1
	v_permlane16_swap_b32_e32 v196, v198
	v_permlane16_swap_b32_e32 v197, v199
	global_store_dwordx4 v[194:195], v[196:199], off
	v_mov_b32_e32 v202, v84
	v_mov_b32_e32 v203, v85
	s_nop 1
	v_permlane16_swap_b32_e32 v200, v202
	v_permlane16_swap_b32_e32 v201, v203
	global_store_dwordx4 v[204:205], v[200:203], off
	s_and_saveexec_b64 s[18:19], s[0:1]
	s_cbranch_execz .LBB0_931
	s_waitcnt lgkmcnt(0)
	v_add_f32_e32 v80, v80, v81
	ds_add_f32 v149, v80
; DI unsigned pk2(float a, float b) { f32x2 v = {a, b}; bf2_t r = __builtin_convertvector(v, bf2_t); return __builtin_bit_cast(unsigned, r); }
; DI float bflo(unsigned u) { return __uint_as_float(u << 16); }
; DI float bfhi(unsigned u) { return __uint_as_float(u & 0xffff0000u); }
; __global__ void __launch_bounds__(512) hybrid_fwd(Params p) {
;     ...
;                       for (int m = 0; m < 4; ++m) { const int rl = ai * 128 + wr * 64 + m * 16 + fr; const size_t ro = (size_t)(pm * 256 + rl) * 1024 + pn * 256 + wc * 32 + 4 * fq;
;                           float ssq = 0.f;
; #pragma unroll
;                           for (int bj = 0; bj < 2; ++bj)
; #pragma unroll
;                               for (int n = 0; n < 2; ++n) { const size_t o = ro + bj * 128 + n * 16; const u32x2 xb = *(const u32x2*)(U + o);
;                                   const f32x4 v = (f32x4){bflo(xb[0]), bfhi(xb[0]), bflo(xb[1]), bfhi(xb[1])} + acc[ai][bj][m][n];
;                                   u32x2 wv; wv[0] = pk2(v[0], v[1]); wv[1] = pk2(v[2], v[3]); *(u32x2*)(X2B + o) = wv;
;                                   ssq += v[0] * v[0] + v[1] * v[1] + v[2] * v[2] + v[3] * v[3]; }
;                           ssq += __shfl_xor(ssq, 16); ssq += __shfl_xor(ssq, 32);
;                           if (fq == 0) __hip_atomic_fetch_add((float*)(shm + 131072) + rl, ssq, __ATOMIC_RELAXED, __HIP_MEMORY_SCOPE_WORKGROUP); } }, vb, panel);
.LBB0_931:
	s_or_b64 exec, exec, s[18:19]
	v_add_u32_e32 v80, s22, v150
	s_waitcnt lgkmcnt(0)
	v_ashrrev_i32_e32 v81, 31, v80
	v_lshlrev_b64 v[80:81], 10, v[80:81]
	v_lshl_add_u64 v[80:81], v[140:141], 0, v[80:81]
	v_lshlrev_b64 v[80:81], 1, v[80:81]
	v_lshl_add_u64 v[82:83], s[20:21], 0, v[80:81]
	v_or_b32_e32 v84, 32, v80
	v_mov_b32_e32 v85, v81
	v_lshl_add_u64 v[86:87], s[20:21], 0, v[84:85]
	v_or_b32_e32 v88, 0x100, v80
	v_mov_b32_e32 v89, v81
	v_lshl_add_u64 v[92:93], s[58:59], 0, v[80:81]
	v_or_b32_e32 v80, 0x120, v80
	v_lshl_add_u64 v[90:91], s[20:21], 0, v[88:89]
	v_lshl_add_u64 v[94:95], s[20:21], 0, v[80:81]
	v_lshl_add_u64 v[84:85], s[58:59], 0, v[84:85]
	v_lshlrev_b32_e32 v96, 16, v82
	v_and_b32_e32 v97, 0xffff0000, v82
	v_lshlrev_b32_e32 v82, 16, v83
	v_and_b32_e32 v83, 0xffff0000, v83
	v_lshlrev_b32_e32 v82, 16, v86
	v_and_b32_e32 v83, 0xffff0000, v86
	v_lshlrev_b32_e32 v96, 16, v90
	v_and_b32_e32 v97, 0xffff0000, v90
	v_lshlrev_b32_e32 v98, 16, v94
	v_and_b32_e32 v99, 0xffff0000, v94
	v_lshlrev_b32_e32 v86, 16, v87
	v_and_b32_e32 v87, 0xffff0000, v87
	v_cvt_pk_bf16_f32 v100, v76, v77
	v_mul_f32_e32 v77, v77, v77
	v_mov_b32_e32 v82, v64
	v_mov_b32_e32 v83, v65
	v_cvt_pk_bf16_f32 v64, v72, v73
	v_mul_f32_e32 v73, v73, v73
	v_lshlrev_b32_e32 v90, 16, v91
	v_and_b32_e32 v91, 0xffff0000, v91
	v_fmac_f32_e32 v77, v76, v76
	v_mul_f32_e32 v76, v69, v69
	v_fmac_f32_e32 v73, v72, v72
	v_lshlrev_b32_e32 v94, 16, v95
	v_and_b32_e32 v95, 0xffff0000, v95
	v_mul_f32_e32 v86, v83, v83
	v_fmac_f32_e32 v77, v78, v78
	v_fmac_f32_e32 v76, v68, v68
	v_fmac_f32_e32 v73, v74, v74
	v_cvt_pk_bf16_f32 v65, v74, v75
	v_fmac_f32_e32 v86, v82, v82
	v_fmac_f32_e32 v77, v79, v79
	v_fmac_f32_e32 v76, v70, v70
	v_fmac_f32_e32 v73, v75, v75
	v_mov_b32_e32 v210, v64
	v_mov_b32_e32 v211, v65
	v_fmac_f32_e32 v86, v66, v66
	v_fmac_f32_e32 v76, v71, v71
	v_add_f32_e32 v64, v77, v73
	v_add_f32_e32 v64, v64, v76
	v_fmac_f32_e32 v86, v67, v67
	v_add_f32_e32 v72, v64, v86
	ds_bpermute_b32 v73, v162, v72
	v_cvt_pk_bf16_f32 v64, v68, v69
	v_cvt_pk_bf16_f32 v65, v70, v71
	v_lshl_add_u64 v[68:69], s[58:59], 0, v[88:89]
	v_mov_b32_e32 v212, v64
	v_mov_b32_e32 v213, v65
	v_lshl_add_u64 v[216:217], v[68:69], 0, v[218:219]
	s_waitcnt lgkmcnt(0)
	v_add_f32_e32 v64, v72, v73
	ds_bpermute_b32 v65, v161, v64
	v_cvt_pk_bf16_f32 v101, v78, v79
	v_cvt_pk_bf16_f32 v68, v82, v83
	v_cvt_pk_bf16_f32 v69, v66, v67
	v_lshl_add_u64 v[66:67], s[58:59], 0, v[80:81]
	v_mov_b32_e32 v208, v100
	v_mov_b32_e32 v209, v101
	v_lshl_add_u64 v[206:207], v[92:93], 0, v[218:219]
	s_nop 1
	v_permlane16_swap_b32_e32 v208, v210
	v_permlane16_swap_b32_e32 v209, v211
	global_store_dwordx4 v[206:207], v[208:211], off
	v_mov_b32_e32 v214, v68
	v_mov_b32_e32 v215, v69
	s_nop 1
	v_permlane16_swap_b32_e32 v212, v214
	v_permlane16_swap_b32_e32 v213, v215
	global_store_dwordx4 v[216:217], v[212:215], off
	s_and_saveexec_b64 s[18:19], s[0:1]
	s_cbranch_execz .LBB0_933
	s_waitcnt lgkmcnt(0)
	v_add_f32_e32 v64, v64, v65
	ds_add_f32 v151, v64
.LBB0_933:
	s_or_b64 exec, exec, s[18:19]
	v_add_u32_e32 v64, s22, v152
	s_waitcnt lgkmcnt(0)
	v_ashrrev_i32_e32 v65, 31, v64
	v_lshlrev_b64 v[64:65], 10, v[64:65]
	v_lshl_add_u64 v[64:65], v[140:141], 0, v[64:65]
	v_lshlrev_b64 v[64:65], 1, v[64:65]
	v_lshl_add_u64 v[66:67], s[20:21], 0, v[64:65]
	v_or_b32_e32 v68, 32, v64
	v_mov_b32_e32 v69, v65
	v_lshl_add_u64 v[70:71], s[20:21], 0, v[68:69]
	v_or_b32_e32 v72, 0x100, v64
	v_mov_b32_e32 v73, v65
	v_lshl_add_u64 v[76:77], s[58:59], 0, v[64:65]
	v_or_b32_e32 v64, 0x120, v64
	v_lshl_add_u64 v[74:75], s[20:21], 0, v[72:73]
	v_lshl_add_u64 v[78:79], s[20:21], 0, v[64:65]
	v_lshl_add_u64 v[68:69], s[58:59], 0, v[68:69]
	v_lshlrev_b32_e32 v80, 16, v66
	v_and_b32_e32 v81, 0xffff0000, v66
	v_lshlrev_b32_e32 v66, 16, v67
	v_and_b32_e32 v67, 0xffff0000, v67
	v_lshlrev_b32_e32 v66, 16, v70
	v_and_b32_e32 v67, 0xffff0000, v70
	v_lshlrev_b32_e32 v80, 16, v74
	v_and_b32_e32 v81, 0xffff0000, v74
	v_lshlrev_b32_e32 v82, 16, v78
	v_and_b32_e32 v83, 0xffff0000, v78
	v_lshlrev_b32_e32 v70, 16, v71
	v_and_b32_e32 v71, 0xffff0000, v71
	v_cvt_pk_bf16_f32 v84, v60, v61
	v_mul_f32_e32 v61, v61, v61
	v_mov_b32_e32 v66, v48
	v_mov_b32_e32 v67, v49
	v_cvt_pk_bf16_f32 v48, v56, v57
	v_mul_f32_e32 v57, v57, v57
	v_lshlrev_b32_e32 v74, 16, v75
	v_and_b32_e32 v75, 0xffff0000, v75
	v_fmac_f32_e32 v61, v60, v60
	v_mul_f32_e32 v60, v53, v53
	v_fmac_f32_e32 v57, v56, v56
	v_lshlrev_b32_e32 v78, 16, v79
	v_and_b32_e32 v79, 0xffff0000, v79
	v_mul_f32_e32 v70, v67, v67
	v_fmac_f32_e32 v61, v62, v62
	v_fmac_f32_e32 v60, v52, v52
	v_fmac_f32_e32 v57, v58, v58
	v_cvt_pk_bf16_f32 v49, v58, v59
	v_fmac_f32_e32 v70, v66, v66
	v_fmac_f32_e32 v61, v63, v63
	v_fmac_f32_e32 v60, v54, v54
	v_fmac_f32_e32 v57, v59, v59
	v_mov_b32_e32 v198, v48
	v_mov_b32_e32 v199, v49
	v_fmac_f32_e32 v70, v50, v50
	v_fmac_f32_e32 v60, v55, v55
	v_add_f32_e32 v48, v61, v57
	v_add_f32_e32 v48, v48, v60
	v_fmac_f32_e32 v70, v51, v51
	v_add_f32_e32 v56, v48, v70
	ds_bpermute_b32 v57, v162, v56
	v_cvt_pk_bf16_f32 v48, v52, v53
	v_cvt_pk_bf16_f32 v49, v54, v55
	v_lshl_add_u64 v[52:53], s[58:59], 0, v[72:73]
	v_mov_b32_e32 v200, v48
	v_mov_b32_e32 v201, v49
	v_lshl_add_u64 v[204:205], v[52:53], 0, v[218:219]
	s_waitcnt lgkmcnt(0)
	v_add_f32_e32 v48, v56, v57
	ds_bpermute_b32 v49, v161, v48
	v_cvt_pk_bf16_f32 v85, v62, v63
	v_cvt_pk_bf16_f32 v52, v66, v67
	v_cvt_pk_bf16_f32 v53, v50, v51
	v_lshl_add_u64 v[50:51], s[58:59], 0, v[64:65]
	v_mov_b32_e32 v196, v84
	v_mov_b32_e32 v197, v85
	v_lshl_add_u64 v[194:195], v[76:77], 0, v[218:219]
	s_nop 1
	v_permlane16_swap_b32_e32 v196, v198
	v_permlane16_swap_b32_e32 v197, v199
	global_store_dwordx4 v[194:195], v[196:199], off
	v_mov_b32_e32 v202, v52
	v_mov_b32_e32 v203, v53
	s_nop 1
	v_permlane16_swap_b32_e32 v200, v202
	v_permlane16_swap_b32_e32 v201, v203
	global_store_dwordx4 v[204:205], v[200:203], off
	s_and_saveexec_b64 s[18:19], s[0:1]
	s_cbranch_execz .LBB0_935
	s_waitcnt lgkmcnt(0)
	v_add_f32_e32 v48, v48, v49
	ds_add_f32 v153, v48
; DI unsigned pk2(float a, float b) { f32x2 v = {a, b}; bf2_t r = __builtin_convertvector(v, bf2_t); return __builtin_bit_cast(unsigned, r); }
; DI float bflo(unsigned u) { return __uint_as_float(u << 16); }
; DI float bfhi(unsigned u) { return __uint_as_float(u & 0xffff0000u); }
; __global__ void __launch_bounds__(512) hybrid_fwd(Params p) {
;     ...
;                       for (int m = 0; m < 4; ++m) { const int rl = ai * 128 + wr * 64 + m * 16 + fr; const size_t ro = (size_t)(pm * 256 + rl) * 1024 + pn * 256 + wc * 32 + 4 * fq;
;                           float ssq = 0.f;
; #pragma unroll
;                           for (int bj = 0; bj < 2; ++bj)
; #pragma unroll
;                               for (int n = 0; n < 2; ++n) { const size_t o = ro + bj * 128 + n * 16; const u32x2 xb = *(const u32x2*)(U + o);
;                                   const f32x4 v = (f32x4){bflo(xb[0]), bfhi(xb[0]), bflo(xb[1]), bfhi(xb[1])} + acc[ai][bj][m][n];
;                                   u32x2 wv; wv[0] = pk2(v[0], v[1]); wv[1] = pk2(v[2], v[3]); *(u32x2*)(X2B + o) = wv;
;                                   ssq += v[0] * v[0] + v[1] * v[1] + v[2] * v[2] + v[3] * v[3]; }
;                           ssq += __shfl_xor(ssq, 16); ssq += __shfl_xor(ssq, 32);
;                           if (fq == 0) __hip_atomic_fetch_add((float*)(shm + 131072) + rl, ssq, __ATOMIC_RELAXED, __HIP_MEMORY_SCOPE_WORKGROUP); } }, vb, panel);
.LBB0_935:
	s_or_b64 exec, exec, s[18:19]
	v_add_u32_e32 v48, s22, v154
	s_waitcnt lgkmcnt(0)
	v_ashrrev_i32_e32 v49, 31, v48
	v_lshlrev_b64 v[48:49], 10, v[48:49]
	v_lshl_add_u64 v[48:49], v[140:141], 0, v[48:49]
	v_lshlrev_b64 v[48:49], 1, v[48:49]
	v_lshl_add_u64 v[50:51], s[20:21], 0, v[48:49]
	v_or_b32_e32 v52, 32, v48
	v_mov_b32_e32 v53, v49
	v_lshl_add_u64 v[54:55], s[20:21], 0, v[52:53]
	v_or_b32_e32 v56, 0x100, v48
	v_mov_b32_e32 v57, v49
	v_lshl_add_u64 v[60:61], s[58:59], 0, v[48:49]
	v_or_b32_e32 v48, 0x120, v48
	v_lshl_add_u64 v[58:59], s[20:21], 0, v[56:57]
	v_lshl_add_u64 v[62:63], s[20:21], 0, v[48:49]
	v_lshl_add_u64 v[52:53], s[58:59], 0, v[52:53]
	v_lshlrev_b32_e32 v64, 16, v50
	v_and_b32_e32 v65, 0xffff0000, v50
	v_lshlrev_b32_e32 v50, 16, v51
	v_and_b32_e32 v51, 0xffff0000, v51
	v_lshlrev_b32_e32 v50, 16, v54
	v_and_b32_e32 v51, 0xffff0000, v54
	v_lshlrev_b32_e32 v64, 16, v58
	v_and_b32_e32 v65, 0xffff0000, v58
	v_lshlrev_b32_e32 v66, 16, v62
	v_and_b32_e32 v67, 0xffff0000, v62
	v_lshlrev_b32_e32 v54, 16, v55
	v_and_b32_e32 v55, 0xffff0000, v55
	v_cvt_pk_bf16_f32 v68, v44, v45
	v_mul_f32_e32 v45, v45, v45
	v_mov_b32_e32 v50, v32
	v_mov_b32_e32 v51, v33
	v_cvt_pk_bf16_f32 v32, v40, v41
	v_mul_f32_e32 v41, v41, v41
	v_lshlrev_b32_e32 v58, 16, v59
	v_and_b32_e32 v59, 0xffff0000, v59
	v_fmac_f32_e32 v45, v44, v44
	v_mul_f32_e32 v44, v37, v37
	v_fmac_f32_e32 v41, v40, v40
	v_lshlrev_b32_e32 v62, 16, v63
	v_and_b32_e32 v63, 0xffff0000, v63
	v_mul_f32_e32 v54, v51, v51
	v_fmac_f32_e32 v45, v46, v46
	v_fmac_f32_e32 v44, v36, v36
	v_fmac_f32_e32 v41, v42, v42
	v_cvt_pk_bf16_f32 v33, v42, v43
	v_fmac_f32_e32 v54, v50, v50
	v_fmac_f32_e32 v45, v47, v47
	v_fmac_f32_e32 v44, v38, v38
	v_fmac_f32_e32 v41, v43, v43
	v_mov_b32_e32 v210, v32
	v_mov_b32_e32 v211, v33
	v_fmac_f32_e32 v54, v34, v34
	v_fmac_f32_e32 v44, v39, v39
	v_add_f32_e32 v32, v45, v41
	v_add_f32_e32 v32, v32, v44
	v_fmac_f32_e32 v54, v35, v35
	v_add_f32_e32 v40, v32, v54
	ds_bpermute_b32 v41, v162, v40
	v_cvt_pk_bf16_f32 v32, v36, v37
	v_cvt_pk_bf16_f32 v33, v38, v39
	v_lshl_add_u64 v[36:37], s[58:59], 0, v[56:57]
	v_mov_b32_e32 v212, v32
	v_mov_b32_e32 v213, v33
	v_lshl_add_u64 v[216:217], v[36:37], 0, v[218:219]
	s_waitcnt lgkmcnt(0)
	v_add_f32_e32 v32, v40, v41
	ds_bpermute_b32 v33, v161, v32
	v_cvt_pk_bf16_f32 v69, v46, v47
	v_cvt_pk_bf16_f32 v36, v50, v51
	v_cvt_pk_bf16_f32 v37, v34, v35
	v_lshl_add_u64 v[34:35], s[58:59], 0, v[48:49]
	v_mov_b32_e32 v208, v68
	v_mov_b32_e32 v209, v69
	v_lshl_add_u64 v[206:207], v[60:61], 0, v[218:219]
	s_nop 1
	v_permlane16_swap_b32_e32 v208, v210
	v_permlane16_swap_b32_e32 v209, v211
	global_store_dwordx4 v[206:207], v[208:211], off
	v_mov_b32_e32 v214, v36
	v_mov_b32_e32 v215, v37
	s_nop 1
	v_permlane16_swap_b32_e32 v212, v214
	v_permlane16_swap_b32_e32 v213, v215
	global_store_dwordx4 v[216:217], v[212:215], off
	s_and_saveexec_b64 s[18:19], s[0:1]
	s_cbranch_execz .LBB0_937
	s_waitcnt lgkmcnt(0)
	v_add_f32_e32 v32, v32, v33
	ds_add_f32 v155, v32
; DI unsigned pk2(float a, float b) { f32x2 v = {a, b}; bf2_t r = __builtin_convertvector(v, bf2_t); return __builtin_bit_cast(unsigned, r); }
; DI float bflo(unsigned u) { return __uint_as_float(u << 16); }
; DI float bfhi(unsigned u) { return __uint_as_float(u & 0xffff0000u); }
; __global__ void __launch_bounds__(512) hybrid_fwd(Params p) {
;     ...
;                       for (int m = 0; m < 4; ++m) { const int rl = ai * 128 + wr * 64 + m * 16 + fr; const size_t ro = (size_t)(pm * 256 + rl) * 1024 + pn * 256 + wc * 32 + 4 * fq;
;                           float ssq = 0.f;
; #pragma unroll
;                           for (int bj = 0; bj < 2; ++bj)
; #pragma unroll
;                               for (int n = 0; n < 2; ++n) { const size_t o = ro + bj * 128 + n * 16; const u32x2 xb = *(const u32x2*)(U + o);
;                                   const f32x4 v = (f32x4){bflo(xb[0]), bfhi(xb[0]), bflo(xb[1]), bfhi(xb[1])} + acc[ai][bj][m][n];
;                                   u32x2 wv; wv[0] = pk2(v[0], v[1]); wv[1] = pk2(v[2], v[3]); *(u32x2*)(X2B + o) = wv;
;                                   ssq += v[0] * v[0] + v[1] * v[1] + v[2] * v[2] + v[3] * v[3]; }
;                           ssq += __shfl_xor(ssq, 16); ssq += __shfl_xor(ssq, 32);
;                           if (fq == 0) __hip_atomic_fetch_add((float*)(shm + 131072) + rl, ssq, __ATOMIC_RELAXED, __HIP_MEMORY_SCOPE_WORKGROUP); } }, vb, panel);
.LBB0_937:
	s_or_b64 exec, exec, s[18:19]
	v_add_u32_e32 v32, s22, v156
	s_waitcnt lgkmcnt(0)
	v_ashrrev_i32_e32 v33, 31, v32
	v_lshlrev_b64 v[32:33], 10, v[32:33]
	v_lshl_add_u64 v[32:33], v[140:141], 0, v[32:33]
	v_lshlrev_b64 v[32:33], 1, v[32:33]
	v_lshl_add_u64 v[34:35], s[20:21], 0, v[32:33]
	v_or_b32_e32 v36, 32, v32
	v_mov_b32_e32 v37, v33
	v_lshl_add_u64 v[38:39], s[20:21], 0, v[36:37]
	v_or_b32_e32 v40, 0x100, v32
	v_mov_b32_e32 v41, v33
	v_lshl_add_u64 v[44:45], s[58:59], 0, v[32:33]
	v_or_b32_e32 v32, 0x120, v32
	v_lshl_add_u64 v[42:43], s[20:21], 0, v[40:41]
	v_lshl_add_u64 v[46:47], s[20:21], 0, v[32:33]
	v_lshl_add_u64 v[36:37], s[58:59], 0, v[36:37]
	v_lshlrev_b32_e32 v48, 16, v34
	v_and_b32_e32 v49, 0xffff0000, v34
	v_lshlrev_b32_e32 v34, 16, v35
	v_and_b32_e32 v35, 0xffff0000, v35
	v_lshlrev_b32_e32 v34, 16, v38
	v_and_b32_e32 v35, 0xffff0000, v38
	v_lshlrev_b32_e32 v48, 16, v42
	v_and_b32_e32 v49, 0xffff0000, v42
	v_lshlrev_b32_e32 v50, 16, v46
	v_and_b32_e32 v51, 0xffff0000, v46
	v_lshlrev_b32_e32 v38, 16, v39
	v_and_b32_e32 v39, 0xffff0000, v39
	v_cvt_pk_bf16_f32 v52, v28, v29
	v_mul_f32_e32 v29, v29, v29
	v_mov_b32_e32 v34, v16
	v_mov_b32_e32 v35, v17
	v_cvt_pk_bf16_f32 v16, v24, v25
	v_mul_f32_e32 v25, v25, v25
	v_lshlrev_b32_e32 v42, 16, v43
	v_and_b32_e32 v43, 0xffff0000, v43
	v_fmac_f32_e32 v29, v28, v28
	v_mul_f32_e32 v28, v21, v21
	v_fmac_f32_e32 v25, v24, v24
	v_lshlrev_b32_e32 v46, 16, v47
	v_and_b32_e32 v47, 0xffff0000, v47
	v_mul_f32_e32 v38, v35, v35
	v_fmac_f32_e32 v29, v30, v30
	v_fmac_f32_e32 v28, v20, v20
	v_fmac_f32_e32 v25, v26, v26
	v_cvt_pk_bf16_f32 v17, v26, v27
	v_fmac_f32_e32 v38, v34, v34
	v_fmac_f32_e32 v29, v31, v31
	v_fmac_f32_e32 v28, v22, v22
	v_fmac_f32_e32 v25, v27, v27
	v_mov_b32_e32 v198, v16
	v_mov_b32_e32 v199, v17
	v_fmac_f32_e32 v38, v18, v18
	v_fmac_f32_e32 v28, v23, v23
	v_add_f32_e32 v16, v29, v25
	v_add_f32_e32 v16, v16, v28
	v_fmac_f32_e32 v38, v19, v19
	v_add_f32_e32 v24, v16, v38
	ds_bpermute_b32 v25, v162, v24
	v_cvt_pk_bf16_f32 v16, v20, v21
	v_cvt_pk_bf16_f32 v17, v22, v23
	v_lshl_add_u64 v[20:21], s[58:59], 0, v[40:41]
	v_mov_b32_e32 v200, v16
	v_mov_b32_e32 v201, v17
	v_lshl_add_u64 v[204:205], v[20:21], 0, v[218:219]
	s_waitcnt lgkmcnt(0)
	v_add_f32_e32 v16, v24, v25
	ds_bpermute_b32 v17, v161, v16
	v_cvt_pk_bf16_f32 v53, v30, v31
	v_cvt_pk_bf16_f32 v20, v34, v35
	v_cvt_pk_bf16_f32 v21, v18, v19
	v_lshl_add_u64 v[18:19], s[58:59], 0, v[32:33]
	v_mov_b32_e32 v196, v52
	v_mov_b32_e32 v197, v53
	v_lshl_add_u64 v[194:195], v[44:45], 0, v[218:219]
	s_nop 1
	v_permlane16_swap_b32_e32 v196, v198
	v_permlane16_swap_b32_e32 v197, v199
	global_store_dwordx4 v[194:195], v[196:199], off
	v_mov_b32_e32 v202, v20
	v_mov_b32_e32 v203, v21
	s_nop 1
	v_permlane16_swap_b32_e32 v200, v202
	v_permlane16_swap_b32_e32 v201, v203
	global_store_dwordx4 v[204:205], v[200:203], off
	s_and_saveexec_b64 s[18:19], s[0:1]
	s_cbranch_execz .LBB0_939
	s_waitcnt lgkmcnt(0)
	v_add_f32_e32 v16, v16, v17
	ds_add_f32 v157, v16
.LBB0_939:
	s_or_b64 exec, exec, s[18:19]
	v_add_u32_e32 v16, s22, v158
	s_waitcnt lgkmcnt(0)
	v_ashrrev_i32_e32 v17, 31, v16
	v_lshlrev_b64 v[16:17], 10, v[16:17]
	v_lshl_add_u64 v[16:17], v[140:141], 0, v[16:17]
	v_lshlrev_b64 v[16:17], 1, v[16:17]
	v_lshl_add_u64 v[18:19], s[20:21], 0, v[16:17]
	v_or_b32_e32 v20, 32, v16
	v_mov_b32_e32 v21, v17
	v_lshl_add_u64 v[22:23], s[20:21], 0, v[20:21]
	v_or_b32_e32 v24, 0x100, v16
	v_mov_b32_e32 v25, v17
	v_lshl_add_u64 v[28:29], s[58:59], 0, v[16:17]
	v_or_b32_e32 v16, 0x120, v16
	v_lshl_add_u64 v[26:27], s[20:21], 0, v[24:25]
	v_lshl_add_u64 v[30:31], s[20:21], 0, v[16:17]
	v_lshl_add_u64 v[20:21], s[58:59], 0, v[20:21]
	v_lshlrev_b32_e32 v32, 16, v18
	v_and_b32_e32 v33, 0xffff0000, v18
	v_lshlrev_b32_e32 v18, 16, v19
	v_and_b32_e32 v19, 0xffff0000, v19
	v_lshlrev_b32_e32 v18, 16, v22
	v_and_b32_e32 v19, 0xffff0000, v22
	v_lshlrev_b32_e32 v32, 16, v26
	v_and_b32_e32 v33, 0xffff0000, v26
	v_lshlrev_b32_e32 v34, 16, v30
	v_and_b32_e32 v35, 0xffff0000, v30
	v_lshlrev_b32_e32 v22, 16, v23
	v_and_b32_e32 v23, 0xffff0000, v23
	v_cvt_pk_bf16_f32 v36, v12, v13
	v_mul_f32_e32 v13, v13, v13
	v_mov_b32_e32 v18, v0
	v_mov_b32_e32 v19, v1
	v_cvt_pk_bf16_f32 v0, v8, v9
	v_mul_f32_e32 v9, v9, v9
	v_lshlrev_b32_e32 v26, 16, v27
	v_and_b32_e32 v27, 0xffff0000, v27
	v_fmac_f32_e32 v13, v12, v12
	v_mul_f32_e32 v12, v5, v5
	v_fmac_f32_e32 v9, v8, v8
	v_lshlrev_b32_e32 v30, 16, v31
	v_and_b32_e32 v31, 0xffff0000, v31
	v_mul_f32_e32 v22, v19, v19
	v_fmac_f32_e32 v13, v14, v14
	v_fmac_f32_e32 v12, v4, v4
	v_fmac_f32_e32 v9, v10, v10
	v_cvt_pk_bf16_f32 v1, v10, v11
	v_fmac_f32_e32 v22, v18, v18
	v_fmac_f32_e32 v13, v15, v15
	v_fmac_f32_e32 v12, v6, v6
	v_fmac_f32_e32 v9, v11, v11
	v_mov_b32_e32 v210, v0
	v_mov_b32_e32 v211, v1
	v_fmac_f32_e32 v22, v2, v2
	v_fmac_f32_e32 v12, v7, v7
	v_add_f32_e32 v0, v13, v9
	v_add_f32_e32 v0, v0, v12
	v_fmac_f32_e32 v22, v3, v3
	v_add_f32_e32 v8, v0, v22
	ds_bpermute_b32 v9, v162, v8
	v_cvt_pk_bf16_f32 v0, v4, v5
	v_cvt_pk_bf16_f32 v1, v6, v7
	v_lshl_add_u64 v[4:5], s[58:59], 0, v[24:25]
	v_mov_b32_e32 v212, v0
	v_mov_b32_e32 v213, v1
	v_lshl_add_u64 v[216:217], v[4:5], 0, v[218:219]
	s_waitcnt lgkmcnt(0)
	v_add_f32_e32 v0, v8, v9
	ds_bpermute_b32 v1, v161, v0
	v_cvt_pk_bf16_f32 v37, v14, v15
	v_cvt_pk_bf16_f32 v4, v18, v19
	v_cvt_pk_bf16_f32 v5, v2, v3
	v_lshl_add_u64 v[2:3], s[58:59], 0, v[16:17]
	v_mov_b32_e32 v208, v36
	v_mov_b32_e32 v209, v37
	v_lshl_add_u64 v[206:207], v[28:29], 0, v[218:219]
	s_nop 1
	v_permlane16_swap_b32_e32 v208, v210
	v_permlane16_swap_b32_e32 v209, v211
	global_store_dwordx4 v[206:207], v[208:211], off
	v_mov_b32_e32 v214, v4
	v_mov_b32_e32 v215, v5
	s_nop 1
	v_permlane16_swap_b32_e32 v212, v214
	v_permlane16_swap_b32_e32 v213, v215
	global_store_dwordx4 v[216:217], v[212:215], off
	s_and_saveexec_b64 s[18:19], s[0:1]
	s_cbranch_execz .LBB0_915
	s_waitcnt lgkmcnt(0)
	v_add_f32_e32 v0, v0, v1
	ds_add_f32 v159, v0
	s_branch .LBB0_915
